# k21 + heavy GEMM K-loops: one static s_setprio 1 for waves 4-7 for the whole loop, per-segment priority flips deleted
# baseline (speedup 1.0000x reference)
.LBB0_669:
	s_add_u32 s19, s34, 0x100
	s_addc_u32 s93, s35, 0
	s_add_u32 s34, s36, 0x100080
	v_mov_b32_e32 v2, 0
	s_addc_u32 s35, s37, 0
	s_mov_b32 s94, -2
	v_mov_b32_e32 v3, v2
	v_mov_b32_e32 v4, v2
	v_mov_b32_e32 v5, v2
	v_mov_b32_e32 v6, v2
	v_mov_b32_e32 v7, v2
	v_mov_b32_e32 v8, v2
	v_mov_b32_e32 v9, v2
	v_mov_b32_e32 v10, v2
	v_mov_b32_e32 v11, v2
	v_mov_b32_e32 v12, v2
	v_mov_b32_e32 v13, v2
	v_mov_b32_e32 v18, v2
	v_mov_b32_e32 v19, v2
	v_mov_b32_e32 v20, v2
	v_mov_b32_e32 v21, v2
	v_mov_b32_e32 v26, v2
	v_mov_b32_e32 v27, v2
	v_mov_b32_e32 v28, v2
	v_mov_b32_e32 v29, v2
	v_mov_b32_e32 v34, v2
	v_mov_b32_e32 v35, v2
	v_mov_b32_e32 v36, v2
	v_mov_b32_e32 v37, v2
	v_mov_b32_e32 v42, v2
	v_mov_b32_e32 v43, v2
	v_mov_b32_e32 v44, v2
	v_mov_b32_e32 v45, v2
	v_mov_b32_e32 v50, v2
	v_mov_b32_e32 v51, v2
	v_mov_b32_e32 v52, v2
	v_mov_b32_e32 v53, v2
	v_mov_b32_e32 v14, v2
	v_mov_b32_e32 v15, v2
	v_mov_b32_e32 v16, v2
	v_mov_b32_e32 v17, v2
	v_mov_b32_e32 v22, v2
	v_mov_b32_e32 v23, v2
	v_mov_b32_e32 v24, v2
	v_mov_b32_e32 v25, v2
	v_mov_b32_e32 v30, v2
	v_mov_b32_e32 v31, v2
	v_mov_b32_e32 v32, v2
	v_mov_b32_e32 v33, v2
	v_mov_b32_e32 v38, v2
	v_mov_b32_e32 v39, v2
	v_mov_b32_e32 v40, v2
	v_mov_b32_e32 v41, v2
	v_mov_b32_e32 v46, v2
	v_mov_b32_e32 v47, v2
	v_mov_b32_e32 v48, v2
	v_mov_b32_e32 v49, v2
	v_mov_b32_e32 v54, v2
	v_mov_b32_e32 v55, v2
	v_mov_b32_e32 v56, v2
	v_mov_b32_e32 v57, v2
	v_mov_b32_e32 v58, v2
	v_mov_b32_e32 v59, v2
	v_mov_b32_e32 v60, v2
	v_mov_b32_e32 v61, v2
	v_mov_b32_e32 v62, v2
	v_mov_b32_e32 v63, v2
	v_mov_b32_e32 v64, v2
	v_mov_b32_e32 v65, v2
	v_mov_b32_e32 v66, v2
	v_mov_b32_e32 v67, v2
	v_mov_b32_e32 v68, v2
	v_mov_b32_e32 v69, v2
	v_mov_b32_e32 v70, v2
	v_mov_b32_e32 v71, v2
	v_mov_b32_e32 v72, v2
	v_mov_b32_e32 v73, v2
	v_mov_b32_e32 v74, v2
	v_mov_b32_e32 v75, v2
	v_mov_b32_e32 v76, v2
	v_mov_b32_e32 v77, v2
	v_mov_b32_e32 v82, v2
	v_mov_b32_e32 v83, v2
	v_mov_b32_e32 v84, v2
	v_mov_b32_e32 v85, v2
	v_mov_b32_e32 v90, v2
	v_mov_b32_e32 v91, v2
	v_mov_b32_e32 v92, v2
	v_mov_b32_e32 v93, v2
	v_mov_b32_e32 v98, v2
	v_mov_b32_e32 v99, v2
	v_mov_b32_e32 v100, v2
	v_mov_b32_e32 v101, v2
	v_mov_b32_e32 v106, v2
	v_mov_b32_e32 v107, v2
	v_mov_b32_e32 v108, v2
	v_mov_b32_e32 v109, v2
	v_mov_b32_e32 v114, v2
	v_mov_b32_e32 v115, v2
	v_mov_b32_e32 v116, v2
	v_mov_b32_e32 v117, v2
	v_mov_b32_e32 v78, v2
	v_mov_b32_e32 v79, v2
	v_mov_b32_e32 v80, v2
	v_mov_b32_e32 v81, v2
	v_mov_b32_e32 v86, v2
	v_mov_b32_e32 v87, v2
	v_mov_b32_e32 v88, v2
	v_mov_b32_e32 v89, v2
	v_mov_b32_e32 v94, v2
	v_mov_b32_e32 v95, v2
	v_mov_b32_e32 v96, v2
	v_mov_b32_e32 v97, v2
	v_mov_b32_e32 v102, v2
	v_mov_b32_e32 v103, v2
	v_mov_b32_e32 v104, v2
	v_mov_b32_e32 v105, v2
	v_mov_b32_e32 v110, v2
	v_mov_b32_e32 v111, v2
	v_mov_b32_e32 v112, v2
	v_mov_b32_e32 v113, v2
	v_mov_b32_e32 v118, v2
	v_mov_b32_e32 v119, v2
	v_mov_b32_e32 v120, v2
	v_mov_b32_e32 v121, v2
	v_mov_b32_e32 v122, v2
	v_mov_b32_e32 v123, v2
	v_mov_b32_e32 v124, v2
	v_mov_b32_e32 v125, v2
	v_mov_b32_e32 v126, v2
	v_mov_b32_e32 v127, v2
	v_mov_b32_e32 v128, v2
	v_mov_b32_e32 v129, v2
	v_readfirstlane_b32 s98, v0
	s_nop 3
	s_lshr_b32 s98, s98, 8
	s_and_b32 s98, s98, 1
	s_cmp_eq_u32 s98, 1
	s_cbranch_scc0 .Lprio_skip_670
	s_setprio 1
.Lprio_skip_670:
.LBB0_670:
	ds_read_b128 v[154:157], v150
	ds_read_b128 v[158:161], v150 offset:1024
	ds_read_b128 v[162:165], v150 offset:2048
	ds_read_b128 v[166:169], v150 offset:3072
	ds_read_b128 v[202:205], v152
	ds_read_b128 v[206:209], v152 offset:1024
	ds_read_b128 v[210:213], v152 offset:2048
	ds_read_b128 v[214:217], v152 offset:3072
	s_add_u32 s28, s34, 0xfff00080
	s_addc_u32 s29, s35, -1
	s_cmp_eq_u32 s94, 60
	s_cselect_b32 s39, s23, s29
	s_cselect_b32 s38, s22, s28
	s_cselect_b32 s37, s21, s93
	s_cselect_b32 s36, s20, s19
	v_lshl_add_u64 v[146:147], s[34:35], 0, v[142:143]
	s_add_i32 m0, s27, 0xc000
	ds_read_b128 v[170:173], v151
	ds_read_b128 v[174:177], v151 offset:1024
	ds_read_b128 v[178:181], v151 offset:2048
	ds_read_b128 v[182:185], v151 offset:3072
	ds_read_b128 v[186:189], v151 offset:4096
	ds_read_b128 v[190:193], v151 offset:5120
	ds_read_b128 v[194:197], v151 offset:6144
	ds_read_b128 v[198:201], v151 offset:7168
	global_load_lds_dwordx4 v[146:147], off
	v_lshl_add_u64 v[146:147], s[34:35], 0, v[140:141]
	s_add_i32 m0, s27, 0xe000
	s_nop 0
	global_load_lds_dwordx4 v[146:147], off
	s_waitcnt vmcnt(8)
	s_waitcnt lgkmcnt(0)
	s_barrier
	v_mfma_f32_16x16x32_bf16 v[126:129], v[154:157], v[170:173], v[126:129]
	v_mfma_f32_16x16x32_bf16 v[122:125], v[162:165], v[170:173], v[122:125]
	v_mfma_f32_16x16x32_bf16 v[118:121], v[154:157], v[178:181], v[118:121]
	v_mfma_f32_16x16x32_bf16 v[110:113], v[162:165], v[178:181], v[110:113]
	v_mfma_f32_16x16x32_bf16 v[102:105], v[154:157], v[186:189], v[102:105]
	v_mfma_f32_16x16x32_bf16 v[94:97], v[162:165], v[186:189], v[94:97]
	v_mfma_f32_16x16x32_bf16 v[86:89], v[154:157], v[194:197], v[86:89]
	v_mfma_f32_16x16x32_bf16 v[78:81], v[162:165], v[194:197], v[78:81]
	v_mfma_f32_16x16x32_bf16 v[126:129], v[158:161], v[174:177], v[126:129]
	v_mfma_f32_16x16x32_bf16 v[122:125], v[166:169], v[174:177], v[122:125]
	v_mfma_f32_16x16x32_bf16 v[118:121], v[158:161], v[182:185], v[118:121]
	v_mfma_f32_16x16x32_bf16 v[110:113], v[166:169], v[182:185], v[110:113]
	v_mfma_f32_16x16x32_bf16 v[102:105], v[158:161], v[190:193], v[102:105]
	v_mfma_f32_16x16x32_bf16 v[94:97], v[166:169], v[190:193], v[94:97]
	v_mfma_f32_16x16x32_bf16 v[86:89], v[158:161], v[198:201], v[86:89]
	v_mfma_f32_16x16x32_bf16 v[78:81], v[166:169], v[198:201], v[78:81]
	v_mfma_f32_16x16x32_bf16 v[114:117], v[202:205], v[170:173], v[114:117]
	v_mfma_f32_16x16x32_bf16 v[106:109], v[210:213], v[170:173], v[106:109]
	v_mfma_f32_16x16x32_bf16 v[98:101], v[202:205], v[178:181], v[98:101]
	v_mfma_f32_16x16x32_bf16 v[90:93], v[210:213], v[178:181], v[90:93]
	v_mfma_f32_16x16x32_bf16 v[82:85], v[202:205], v[186:189], v[82:85]
	v_mfma_f32_16x16x32_bf16 v[74:77], v[210:213], v[186:189], v[74:77]
	v_mfma_f32_16x16x32_bf16 v[70:73], v[202:205], v[194:197], v[70:73]
	v_mfma_f32_16x16x32_bf16 v[66:69], v[210:213], v[194:197], v[66:69]
	v_mfma_f32_16x16x32_bf16 v[114:117], v[206:209], v[174:177], v[114:117]
	v_mfma_f32_16x16x32_bf16 v[106:109], v[214:217], v[174:177], v[106:109]
	v_mfma_f32_16x16x32_bf16 v[98:101], v[206:209], v[182:185], v[98:101]
	v_mfma_f32_16x16x32_bf16 v[90:93], v[214:217], v[182:185], v[90:93]
	v_mfma_f32_16x16x32_bf16 v[82:85], v[206:209], v[190:193], v[82:85]
	v_mfma_f32_16x16x32_bf16 v[74:77], v[214:217], v[190:193], v[74:77]
	v_mfma_f32_16x16x32_bf16 v[70:73], v[206:209], v[198:201], v[70:73]
	v_mfma_f32_16x16x32_bf16 v[66:69], v[214:217], v[198:201], v[66:69]
	s_barrier
	ds_read_b128 v[170:173], v151 offset:16384
	ds_read_b128 v[174:177], v151 offset:17408
	ds_read_b128 v[178:181], v151 offset:18432
	ds_read_b128 v[182:185], v151 offset:19456
	ds_read_b128 v[186:189], v151 offset:20480
	ds_read_b128 v[190:193], v151 offset:21504
	ds_read_b128 v[194:197], v151 offset:22528
	ds_read_b128 v[198:201], v151 offset:23552
	s_add_i32 s28, s85, s74
	v_lshl_add_u64 v[146:147], s[36:37], 0, v[134:135]
	s_mov_b32 m0, s28
	s_nop 0
	global_load_lds_dwordx4 v[146:147], off
	v_lshl_add_u64 v[218:219], s[36:37], 0, v[130:131]
	s_add_i32 m0, s28, 0x2000
	s_nop 0
	global_load_lds_dwordx4 v[218:219], off
	s_mov_b32 m0, s27
	v_lshl_add_u64 v[220:221], s[38:39], 0, v[136:137]
	global_load_lds_dwordx4 v[220:221], off
	v_lshl_add_u64 v[222:223], s[38:39], 0, v[132:133]
	s_mov_b32 m0, s76
	s_nop 0
	global_load_lds_dwordx4 v[222:223], off
	s_add_u32 s28, s36, 0x100000
	s_addc_u32 s29, s37, 0
	s_add_i32 s95, s86, s74
	v_lshl_add_u64 v[226:227], s[28:29], 0, v[134:135]
	s_mov_b32 m0, s95
	s_nop 0
	global_load_lds_dwordx4 v[226:227], off
	v_lshl_add_u64 v[226:227], s[28:29], 0, v[130:131]
	s_add_i32 m0, s95, 0x2000
	s_nop 0
	global_load_lds_dwordx4 v[226:227], off
	s_waitcnt vmcnt(8)
	s_waitcnt lgkmcnt(0)
	s_barrier
	v_mfma_f32_16x16x32_bf16 v[62:65], v[154:157], v[170:173], v[62:65]
	v_mfma_f32_16x16x32_bf16 v[58:61], v[162:165], v[170:173], v[58:61]
	v_mfma_f32_16x16x32_bf16 v[54:57], v[154:157], v[178:181], v[54:57]
	v_mfma_f32_16x16x32_bf16 v[46:49], v[162:165], v[178:181], v[46:49]
	v_mfma_f32_16x16x32_bf16 v[38:41], v[154:157], v[186:189], v[38:41]
	v_mfma_f32_16x16x32_bf16 v[30:33], v[162:165], v[186:189], v[30:33]
	v_mfma_f32_16x16x32_bf16 v[22:25], v[154:157], v[194:197], v[22:25]
	v_mfma_f32_16x16x32_bf16 v[14:17], v[162:165], v[194:197], v[14:17]
	v_mfma_f32_16x16x32_bf16 v[62:65], v[158:161], v[174:177], v[62:65]
	v_mfma_f32_16x16x32_bf16 v[58:61], v[166:169], v[174:177], v[58:61]
	v_mfma_f32_16x16x32_bf16 v[54:57], v[158:161], v[182:185], v[54:57]
	v_mfma_f32_16x16x32_bf16 v[46:49], v[166:169], v[182:185], v[46:49]
	v_mfma_f32_16x16x32_bf16 v[38:41], v[158:161], v[190:193], v[38:41]
	v_mfma_f32_16x16x32_bf16 v[30:33], v[166:169], v[190:193], v[30:33]
	v_mfma_f32_16x16x32_bf16 v[22:25], v[158:161], v[198:201], v[22:25]
	v_mfma_f32_16x16x32_bf16 v[14:17], v[166:169], v[198:201], v[14:17]
	v_mfma_f32_16x16x32_bf16 v[50:53], v[202:205], v[170:173], v[50:53]
	v_mfma_f32_16x16x32_bf16 v[42:45], v[210:213], v[170:173], v[42:45]
	v_mfma_f32_16x16x32_bf16 v[34:37], v[202:205], v[178:181], v[34:37]
	v_mfma_f32_16x16x32_bf16 v[26:29], v[210:213], v[178:181], v[26:29]
	v_mfma_f32_16x16x32_bf16 v[18:21], v[202:205], v[186:189], v[18:21]
	v_mfma_f32_16x16x32_bf16 v[10:13], v[210:213], v[186:189], v[10:13]
	v_mfma_f32_16x16x32_bf16 v[6:9], v[202:205], v[194:197], v[6:9]
	v_mfma_f32_16x16x32_bf16 v[2:5], v[210:213], v[194:197], v[2:5]
	v_mfma_f32_16x16x32_bf16 v[50:53], v[206:209], v[174:177], v[50:53]
	v_mfma_f32_16x16x32_bf16 v[42:45], v[214:217], v[174:177], v[42:45]
	v_mfma_f32_16x16x32_bf16 v[34:37], v[206:209], v[182:185], v[34:37]
	v_mfma_f32_16x16x32_bf16 v[26:29], v[214:217], v[182:185], v[26:29]
	v_mfma_f32_16x16x32_bf16 v[18:21], v[206:209], v[190:193], v[18:21]
	v_mfma_f32_16x16x32_bf16 v[10:13], v[214:217], v[190:193], v[10:13]
	v_mfma_f32_16x16x32_bf16 v[6:9], v[206:209], v[198:201], v[6:9]
	v_mfma_f32_16x16x32_bf16 v[2:5], v[214:217], v[198:201], v[2:5]
	s_add_i32 s95, 0, 0x18000
	v_add_u32_e32 v153, s95, v148
	s_barrier
	ds_read_b128 v[154:157], v153
	ds_read_b128 v[158:161], v153 offset:1024
	ds_read_b128 v[162:165], v153 offset:2048
	ds_read_b128 v[166:169], v153 offset:3072
	ds_read_b128 v[202:205], v153 offset:16384
	ds_read_b128 v[206:209], v153 offset:17408
	ds_read_b128 v[210:213], v153 offset:18432
	ds_read_b128 v[214:217], v153 offset:19456
	s_add_u32 s28, s38, 0x100000
	s_addc_u32 s29, s39, 0
	s_mov_b32 m0, s77
	v_lshl_add_u64 v[226:227], s[28:29], 0, v[136:137]
	ds_read_b128 v[170:173], v151 offset:32768
	ds_read_b128 v[174:177], v151 offset:33792
	ds_read_b128 v[178:181], v151 offset:34816
	ds_read_b128 v[182:185], v151 offset:35840
	ds_read_b128 v[186:189], v151 offset:36864
	ds_read_b128 v[190:193], v151 offset:37888
	ds_read_b128 v[194:197], v151 offset:38912
	ds_read_b128 v[198:201], v151 offset:39936
	global_load_lds_dwordx4 v[226:227], off
	v_lshl_add_u64 v[226:227], s[28:29], 0, v[132:133]
	s_mov_b32 m0, s78
	s_nop 0
	global_load_lds_dwordx4 v[226:227], off
	s_waitcnt vmcnt(8)
	s_waitcnt lgkmcnt(0)
	s_barrier
	v_mfma_f32_16x16x32_bf16 v[126:129], v[154:157], v[170:173], v[126:129]
	v_mfma_f32_16x16x32_bf16 v[122:125], v[162:165], v[170:173], v[122:125]
	v_mfma_f32_16x16x32_bf16 v[118:121], v[154:157], v[178:181], v[118:121]
	v_mfma_f32_16x16x32_bf16 v[110:113], v[162:165], v[178:181], v[110:113]
	v_mfma_f32_16x16x32_bf16 v[102:105], v[154:157], v[186:189], v[102:105]
	v_mfma_f32_16x16x32_bf16 v[94:97], v[162:165], v[186:189], v[94:97]
	v_mfma_f32_16x16x32_bf16 v[86:89], v[154:157], v[194:197], v[86:89]
	v_mfma_f32_16x16x32_bf16 v[78:81], v[162:165], v[194:197], v[78:81]
	v_mfma_f32_16x16x32_bf16 v[126:129], v[158:161], v[174:177], v[126:129]
	v_mfma_f32_16x16x32_bf16 v[122:125], v[166:169], v[174:177], v[122:125]
	v_mfma_f32_16x16x32_bf16 v[118:121], v[158:161], v[182:185], v[118:121]
	v_mfma_f32_16x16x32_bf16 v[110:113], v[166:169], v[182:185], v[110:113]
	v_mfma_f32_16x16x32_bf16 v[102:105], v[158:161], v[190:193], v[102:105]
	v_mfma_f32_16x16x32_bf16 v[94:97], v[166:169], v[190:193], v[94:97]
	v_mfma_f32_16x16x32_bf16 v[86:89], v[158:161], v[198:201], v[86:89]
	v_mfma_f32_16x16x32_bf16 v[78:81], v[166:169], v[198:201], v[78:81]
	v_mfma_f32_16x16x32_bf16 v[114:117], v[202:205], v[170:173], v[114:117]
	v_mfma_f32_16x16x32_bf16 v[106:109], v[210:213], v[170:173], v[106:109]
	v_mfma_f32_16x16x32_bf16 v[98:101], v[202:205], v[178:181], v[98:101]
	v_mfma_f32_16x16x32_bf16 v[90:93], v[210:213], v[178:181], v[90:93]
	v_mfma_f32_16x16x32_bf16 v[82:85], v[202:205], v[186:189], v[82:85]
	v_mfma_f32_16x16x32_bf16 v[74:77], v[210:213], v[186:189], v[74:77]
	v_mfma_f32_16x16x32_bf16 v[70:73], v[202:205], v[194:197], v[70:73]
	v_mfma_f32_16x16x32_bf16 v[66:69], v[210:213], v[194:197], v[66:69]
	v_mfma_f32_16x16x32_bf16 v[114:117], v[206:209], v[174:177], v[114:117]
	v_mfma_f32_16x16x32_bf16 v[106:109], v[214:217], v[174:177], v[106:109]
	v_mfma_f32_16x16x32_bf16 v[98:101], v[206:209], v[182:185], v[98:101]
	v_mfma_f32_16x16x32_bf16 v[90:93], v[214:217], v[182:185], v[90:93]
	v_mfma_f32_16x16x32_bf16 v[82:85], v[206:209], v[190:193], v[82:85]
	v_mfma_f32_16x16x32_bf16 v[74:77], v[214:217], v[190:193], v[74:77]
	v_mfma_f32_16x16x32_bf16 v[70:73], v[206:209], v[198:201], v[70:73]
	v_mfma_f32_16x16x32_bf16 v[66:69], v[214:217], v[198:201], v[66:69]
	s_barrier
	ds_read_b128 v[170:173], v151 offset:49152
	ds_read_b128 v[174:177], v151 offset:50176
	ds_read_b128 v[178:181], v151 offset:51200
	ds_read_b128 v[182:185], v151 offset:52224
	ds_read_b128 v[186:189], v151 offset:53248
	ds_read_b128 v[190:193], v151 offset:54272
	ds_read_b128 v[194:197], v151 offset:55296
	ds_read_b128 v[198:201], v151 offset:56320
	s_add_i32 s38, 0, 0x1c000
	s_add_i32 s28, s95, s74
	v_lshl_add_u64 v[146:147], v[146:147], 0, s[0:1]
	s_mov_b32 m0, s28
	s_nop 0
	global_load_lds_dwordx4 v[146:147], off
	v_lshl_add_u64 v[146:147], v[218:219], 0, s[0:1]
	s_add_i32 m0, s28, 0x2000
	s_nop 0
	global_load_lds_dwordx4 v[146:147], off
	s_mov_b32 m0, s80
	v_lshl_add_u64 v[146:147], v[220:221], 0, s[0:1]
	global_load_lds_dwordx4 v[146:147], off
	v_lshl_add_u64 v[146:147], v[222:223], 0, s[0:1]
	s_mov_b32 m0, s81
	s_nop 0
	global_load_lds_dwordx4 v[146:147], off
	s_add_u32 s28, s36, 0x100080
	s_addc_u32 s29, s37, 0
	s_add_i32 s36, s38, s74
	v_lshl_add_u64 v[146:147], s[28:29], 0, v[134:135]
	s_mov_b32 m0, s36
	s_nop 0
	global_load_lds_dwordx4 v[146:147], off
	v_lshl_add_u64 v[146:147], s[28:29], 0, v[130:131]
	s_add_i32 m0, s36, 0x2000
	s_nop 0
	global_load_lds_dwordx4 v[146:147], off
	s_waitcnt vmcnt(8)
	s_waitcnt lgkmcnt(0)
	s_barrier
	v_mfma_f32_16x16x32_bf16 v[62:65], v[154:157], v[170:173], v[62:65]
	v_mfma_f32_16x16x32_bf16 v[58:61], v[162:165], v[170:173], v[58:61]
	v_mfma_f32_16x16x32_bf16 v[54:57], v[154:157], v[178:181], v[54:57]
	v_mfma_f32_16x16x32_bf16 v[46:49], v[162:165], v[178:181], v[46:49]
	v_mfma_f32_16x16x32_bf16 v[38:41], v[154:157], v[186:189], v[38:41]
	v_mfma_f32_16x16x32_bf16 v[30:33], v[162:165], v[186:189], v[30:33]
	v_mfma_f32_16x16x32_bf16 v[22:25], v[154:157], v[194:197], v[22:25]
	v_mfma_f32_16x16x32_bf16 v[14:17], v[162:165], v[194:197], v[14:17]
	v_mfma_f32_16x16x32_bf16 v[62:65], v[158:161], v[174:177], v[62:65]
	v_mfma_f32_16x16x32_bf16 v[58:61], v[166:169], v[174:177], v[58:61]
	v_mfma_f32_16x16x32_bf16 v[54:57], v[158:161], v[182:185], v[54:57]
	v_mfma_f32_16x16x32_bf16 v[46:49], v[166:169], v[182:185], v[46:49]
	v_mfma_f32_16x16x32_bf16 v[38:41], v[158:161], v[190:193], v[38:41]
	v_mfma_f32_16x16x32_bf16 v[30:33], v[166:169], v[190:193], v[30:33]
	v_mfma_f32_16x16x32_bf16 v[22:25], v[158:161], v[198:201], v[22:25]
	v_mfma_f32_16x16x32_bf16 v[14:17], v[166:169], v[198:201], v[14:17]
	v_mfma_f32_16x16x32_bf16 v[50:53], v[202:205], v[170:173], v[50:53]
	v_mfma_f32_16x16x32_bf16 v[42:45], v[210:213], v[170:173], v[42:45]
	v_mfma_f32_16x16x32_bf16 v[34:37], v[202:205], v[178:181], v[34:37]
	v_mfma_f32_16x16x32_bf16 v[26:29], v[210:213], v[178:181], v[26:29]
	v_mfma_f32_16x16x32_bf16 v[18:21], v[202:205], v[186:189], v[18:21]
	v_mfma_f32_16x16x32_bf16 v[10:13], v[210:213], v[186:189], v[10:13]
	v_mfma_f32_16x16x32_bf16 v[6:9], v[202:205], v[194:197], v[6:9]
	v_mfma_f32_16x16x32_bf16 v[2:5], v[210:213], v[194:197], v[2:5]
	v_mfma_f32_16x16x32_bf16 v[50:53], v[206:209], v[174:177], v[50:53]
	v_mfma_f32_16x16x32_bf16 v[42:45], v[214:217], v[174:177], v[42:45]
	v_mfma_f32_16x16x32_bf16 v[34:37], v[206:209], v[182:185], v[34:37]
	v_mfma_f32_16x16x32_bf16 v[26:29], v[214:217], v[182:185], v[26:29]
	v_mfma_f32_16x16x32_bf16 v[18:21], v[206:209], v[190:193], v[18:21]
	v_mfma_f32_16x16x32_bf16 v[10:13], v[214:217], v[190:193], v[10:13]
	v_mfma_f32_16x16x32_bf16 v[6:9], v[206:209], v[198:201], v[6:9]
	v_mfma_f32_16x16x32_bf16 v[2:5], v[214:217], v[198:201], v[2:5]
	s_add_i32 s94, s94, 2
	s_add_u32 s19, s19, 0x100
	s_addc_u32 s93, s93, 0
	s_add_u32 s34, s34, 0x100
	s_addc_u32 s35, s35, 0
	s_cmp_gt_u32 s94, 61
	s_barrier
	s_cbranch_scc0 .LBB0_670
	s_setprio 0
	s_cmp_lt_i32 s92, 2
	s_cbranch_scc1 .LBB0_675
	s_cmp_eq_u32 s92, 2
	s_mov_b64 s[34:35], -1
	s_cbranch_scc0 .LBB0_674
	v_lshl_add_u32 v146, s26, 8, v1
	v_or_b32_e32 v156, 16, v146
	v_ashrrev_i32_e32 v147, 31, v146
	v_ashrrev_i32_e32 v157, 31, v156
	v_lshlrev_b64 v[154:155], 10, v[146:147]
	v_lshlrev_b64 v[156:157], 10, v[156:157]
	v_lshl_add_u64 v[154:155], v[138:139], 0, v[154:155]
	v_lshl_add_u64 v[156:157], v[138:139], 0, v[156:157]
	global_store_dwordx4 v[154:155], v[126:129], off
	global_store_dwordx4 v[154:155], v[122:125], off offset:16
	global_store_dwordx4 v[154:155], v[114:117], off offset:512
	global_store_dwordx4 v[154:155], v[106:109], off offset:528
	global_store_dwordx4 v[156:157], v[118:121], off
	global_store_dwordx4 v[156:157], v[110:113], off offset:16
	global_store_dwordx4 v[156:157], v[98:101], off offset:512
	global_store_dwordx4 v[156:157], v[90:93], off offset:528
	v_or_b32_e32 v156, 32, v146
	v_ashrrev_i32_e32 v157, 31, v156
	v_lshlrev_b64 v[156:157], 10, v[156:157]
	v_or_b32_e32 v146, 48, v146
	v_lshl_add_u64 v[156:157], v[138:139], 0, v[156:157]
	v_ashrrev_i32_e32 v147, 31, v146
	global_store_dwordx4 v[156:157], v[102:105], off
	global_store_dwordx4 v[156:157], v[94:97], off offset:16
	global_store_dwordx4 v[156:157], v[82:85], off offset:512
	global_store_dwordx4 v[156:157], v[74:77], off offset:528
	v_lshlrev_b64 v[146:147], 10, v[146:147]
	v_add_co_u32_e32 v156, vcc, s87, v154
	v_lshl_add_u64 v[146:147], v[138:139], 0, v[146:147]
	s_mov_b64 s[28:29], 0x20000
	v_addc_co_u32_e32 v157, vcc, 0, v155, vcc
	global_store_dwordx4 v[146:147], v[86:89], off
	global_store_dwordx4 v[146:147], v[78:81], off offset:16
	global_store_dwordx4 v[146:147], v[70:73], off offset:512
	global_store_dwordx4 v[146:147], v[66:69], off offset:528
	v_lshl_add_u64 v[146:147], v[154:155], 0, s[28:29]
	global_store_dwordx4 v[156:157], v[62:65], off
	global_store_dwordx4 v[146:147], v[58:61], off offset:16
	global_store_dwordx4 v[146:147], v[50:53], off offset:512
	global_store_dwordx4 v[146:147], v[42:45], off offset:528
	v_add_co_u32_e32 v156, vcc, s88, v154
	v_lshl_add_u64 v[146:147], v[154:155], 0, s[6:7]
	s_nop 0
	v_addc_co_u32_e32 v157, vcc, 0, v155, vcc
	global_store_dwordx4 v[156:157], v[54:57], off
	global_store_dwordx4 v[146:147], v[46:49], off offset:16
	global_store_dwordx4 v[146:147], v[34:37], off offset:512
	global_store_dwordx4 v[146:147], v[26:29], off offset:528
	v_add_co_u32_e32 v156, vcc, s89, v154
	v_lshl_add_u64 v[146:147], v[154:155], 0, s[12:13]
	s_nop 0
	v_addc_co_u32_e32 v157, vcc, 0, v155, vcc
	global_store_dwordx4 v[156:157], v[38:41], off
	global_store_dwordx4 v[146:147], v[30:33], off offset:16
	global_store_dwordx4 v[146:147], v[18:21], off offset:512
	global_store_dwordx4 v[146:147], v[10:13], off offset:528
	v_lshl_add_u64 v[146:147], v[154:155], 0, s[14:15]
	v_add_co_u32_e32 v154, vcc, 0x2c000, v154
	s_mov_b64 s[34:35], 0
	s_nop 0
	v_addc_co_u32_e32 v155, vcc, 0, v155, vcc
	global_store_dwordx4 v[154:155], v[22:25], off
	global_store_dwordx4 v[146:147], v[14:17], off offset:16
	global_store_dwordx4 v[146:147], v[6:9], off offset:512
	global_store_dwordx4 v[146:147], v[2:5], off offset:528

.LBB0_2484:
	s_add_u32 s39, s52, 0x100
	s_addc_u32 s41, s53, 0
	s_add_u32 s50, s50, 0x100080
	v_mov_b32_e32 v2, 0
	s_addc_u32 s51, s51, 0
	s_mov_b32 s81, -2
	v_mov_b32_e32 v3, v2
	v_mov_b32_e32 v4, v2
	v_mov_b32_e32 v5, v2
	v_mov_b32_e32 v6, v2
	v_mov_b32_e32 v7, v2
	v_mov_b32_e32 v8, v2
	v_mov_b32_e32 v9, v2
	v_mov_b32_e32 v10, v2
	v_mov_b32_e32 v11, v2
	v_mov_b32_e32 v12, v2
	v_mov_b32_e32 v13, v2
	v_mov_b32_e32 v18, v2
	v_mov_b32_e32 v19, v2
	v_mov_b32_e32 v20, v2
	v_mov_b32_e32 v21, v2
	v_mov_b32_e32 v26, v2
	v_mov_b32_e32 v27, v2
	v_mov_b32_e32 v28, v2
	v_mov_b32_e32 v29, v2
	v_mov_b32_e32 v34, v2
	v_mov_b32_e32 v35, v2
	v_mov_b32_e32 v36, v2
	v_mov_b32_e32 v37, v2
	v_mov_b32_e32 v42, v2
	v_mov_b32_e32 v43, v2
	v_mov_b32_e32 v44, v2
	v_mov_b32_e32 v45, v2
	v_mov_b32_e32 v50, v2
	v_mov_b32_e32 v51, v2
	v_mov_b32_e32 v52, v2
	v_mov_b32_e32 v53, v2
	v_mov_b32_e32 v14, v2
	v_mov_b32_e32 v15, v2
	v_mov_b32_e32 v16, v2
	v_mov_b32_e32 v17, v2
	v_mov_b32_e32 v22, v2
	v_mov_b32_e32 v23, v2
	v_mov_b32_e32 v24, v2
	v_mov_b32_e32 v25, v2
	v_mov_b32_e32 v30, v2
	v_mov_b32_e32 v31, v2
	v_mov_b32_e32 v32, v2
	v_mov_b32_e32 v33, v2
	v_mov_b32_e32 v38, v2
	v_mov_b32_e32 v39, v2
	v_mov_b32_e32 v40, v2
	v_mov_b32_e32 v41, v2
	v_mov_b32_e32 v46, v2
	v_mov_b32_e32 v47, v2
	v_mov_b32_e32 v48, v2
	v_mov_b32_e32 v49, v2
	v_mov_b32_e32 v54, v2
	v_mov_b32_e32 v55, v2
	v_mov_b32_e32 v56, v2
	v_mov_b32_e32 v57, v2
	v_mov_b32_e32 v58, v2
	v_mov_b32_e32 v59, v2
	v_mov_b32_e32 v60, v2
	v_mov_b32_e32 v61, v2
	v_mov_b32_e32 v62, v2
	v_mov_b32_e32 v63, v2
	v_mov_b32_e32 v64, v2
	v_mov_b32_e32 v65, v2
	v_mov_b32_e32 v66, v2
	v_mov_b32_e32 v67, v2
	v_mov_b32_e32 v68, v2
	v_mov_b32_e32 v69, v2
	v_mov_b32_e32 v70, v2
	v_mov_b32_e32 v71, v2
	v_mov_b32_e32 v72, v2
	v_mov_b32_e32 v73, v2
	v_mov_b32_e32 v78, v2
	v_mov_b32_e32 v79, v2
	v_mov_b32_e32 v80, v2
	v_mov_b32_e32 v81, v2
	v_mov_b32_e32 v86, v2
	v_mov_b32_e32 v87, v2
	v_mov_b32_e32 v88, v2
	v_mov_b32_e32 v89, v2
	v_mov_b32_e32 v94, v2
	v_mov_b32_e32 v95, v2
	v_mov_b32_e32 v96, v2
	v_mov_b32_e32 v97, v2
	v_mov_b32_e32 v102, v2
	v_mov_b32_e32 v103, v2
	v_mov_b32_e32 v104, v2
	v_mov_b32_e32 v105, v2
	v_mov_b32_e32 v110, v2
	v_mov_b32_e32 v111, v2
	v_mov_b32_e32 v112, v2
	v_mov_b32_e32 v113, v2
	v_mov_b32_e32 v118, v2
	v_mov_b32_e32 v119, v2
	v_mov_b32_e32 v120, v2
	v_mov_b32_e32 v121, v2
	v_mov_b32_e32 v74, v2
	v_mov_b32_e32 v75, v2
	v_mov_b32_e32 v76, v2
	v_mov_b32_e32 v77, v2
	v_mov_b32_e32 v82, v2
	v_mov_b32_e32 v83, v2
	v_mov_b32_e32 v84, v2
	v_mov_b32_e32 v85, v2
	v_mov_b32_e32 v90, v2
	v_mov_b32_e32 v91, v2
	v_mov_b32_e32 v92, v2
	v_mov_b32_e32 v93, v2
	v_mov_b32_e32 v98, v2
	v_mov_b32_e32 v99, v2
	v_mov_b32_e32 v100, v2
	v_mov_b32_e32 v101, v2
	v_mov_b32_e32 v106, v2
	v_mov_b32_e32 v107, v2
	v_mov_b32_e32 v108, v2
	v_mov_b32_e32 v109, v2
	v_mov_b32_e32 v114, v2
	v_mov_b32_e32 v115, v2
	v_mov_b32_e32 v116, v2
	v_mov_b32_e32 v117, v2
	v_mov_b32_e32 v122, v2
	v_mov_b32_e32 v123, v2
	v_mov_b32_e32 v124, v2
	v_mov_b32_e32 v125, v2
	v_mov_b32_e32 v126, v2
	v_mov_b32_e32 v127, v2
	v_mov_b32_e32 v128, v2
	v_mov_b32_e32 v129, v2
	v_readfirstlane_b32 s98, v0
	s_nop 3
	s_lshr_b32 s98, s98, 8
	s_and_b32 s98, s98, 1
	s_cmp_eq_u32 s98, 1
	s_cbranch_scc0 .Lprio_skip_2485
	s_setprio 1
.Lprio_skip_2485:
.LBB0_2485:
	ds_read_b128 v[152:155], v148
	ds_read_b128 v[156:159], v148 offset:1024
	ds_read_b128 v[160:163], v148 offset:2048
	ds_read_b128 v[164:167], v148 offset:3072
	ds_read_b128 v[200:203], v150
	ds_read_b128 v[204:207], v150 offset:1024
	ds_read_b128 v[208:211], v150 offset:2048
	ds_read_b128 v[212:215], v150 offset:3072
	s_add_u32 s28, s50, 0xfff00080
	s_addc_u32 s29, s51, -1
	s_cmp_eq_u32 s81, 60
	s_cselect_b32 s55, s45, s29
	s_cselect_b32 s54, s44, s28
	s_cselect_b32 s53, s47, s41
	s_cselect_b32 s52, s46, s39
	v_lshl_add_u64 v[144:145], s[50:51], 0, v[140:141]
	s_add_i32 m0, s49, 0xc000
	ds_read_b128 v[168:171], v149
	ds_read_b128 v[172:175], v149 offset:1024
	ds_read_b128 v[176:179], v149 offset:2048
	ds_read_b128 v[180:183], v149 offset:3072
	ds_read_b128 v[184:187], v149 offset:4096
	ds_read_b128 v[188:191], v149 offset:5120
	ds_read_b128 v[192:195], v149 offset:6144
	ds_read_b128 v[196:199], v149 offset:7168
	global_load_lds_dwordx4 v[144:145], off
	v_lshl_add_u64 v[144:145], s[50:51], 0, v[138:139]
	s_add_i32 m0, s49, 0xe000
	s_nop 0
	global_load_lds_dwordx4 v[144:145], off
	s_waitcnt vmcnt(8)
	s_waitcnt lgkmcnt(0)
	s_barrier
	v_mfma_f32_16x16x32_bf16 v[126:129], v[152:155], v[168:171], v[126:129]
	v_mfma_f32_16x16x32_bf16 v[122:125], v[160:163], v[168:171], v[122:125]
	v_mfma_f32_16x16x32_bf16 v[114:117], v[152:155], v[176:179], v[114:117]
	v_mfma_f32_16x16x32_bf16 v[106:109], v[160:163], v[176:179], v[106:109]
	v_mfma_f32_16x16x32_bf16 v[98:101], v[152:155], v[184:187], v[98:101]
	v_mfma_f32_16x16x32_bf16 v[90:93], v[160:163], v[184:187], v[90:93]
	v_mfma_f32_16x16x32_bf16 v[82:85], v[152:155], v[192:195], v[82:85]
	v_mfma_f32_16x16x32_bf16 v[74:77], v[160:163], v[192:195], v[74:77]
	v_mfma_f32_16x16x32_bf16 v[126:129], v[156:159], v[172:175], v[126:129]
	v_mfma_f32_16x16x32_bf16 v[122:125], v[164:167], v[172:175], v[122:125]
	v_mfma_f32_16x16x32_bf16 v[114:117], v[156:159], v[180:183], v[114:117]
	v_mfma_f32_16x16x32_bf16 v[106:109], v[164:167], v[180:183], v[106:109]
	v_mfma_f32_16x16x32_bf16 v[98:101], v[156:159], v[188:191], v[98:101]
	v_mfma_f32_16x16x32_bf16 v[90:93], v[164:167], v[188:191], v[90:93]
	v_mfma_f32_16x16x32_bf16 v[82:85], v[156:159], v[196:199], v[82:85]
	v_mfma_f32_16x16x32_bf16 v[74:77], v[164:167], v[196:199], v[74:77]
	v_mfma_f32_16x16x32_bf16 v[118:121], v[200:203], v[168:171], v[118:121]
	v_mfma_f32_16x16x32_bf16 v[110:113], v[208:211], v[168:171], v[110:113]
	v_mfma_f32_16x16x32_bf16 v[102:105], v[200:203], v[176:179], v[102:105]
	v_mfma_f32_16x16x32_bf16 v[94:97], v[208:211], v[176:179], v[94:97]
	v_mfma_f32_16x16x32_bf16 v[86:89], v[200:203], v[184:187], v[86:89]
	v_mfma_f32_16x16x32_bf16 v[78:81], v[208:211], v[184:187], v[78:81]
	v_mfma_f32_16x16x32_bf16 v[70:73], v[200:203], v[192:195], v[70:73]
	v_mfma_f32_16x16x32_bf16 v[66:69], v[208:211], v[192:195], v[66:69]
	v_mfma_f32_16x16x32_bf16 v[118:121], v[204:207], v[172:175], v[118:121]
	v_mfma_f32_16x16x32_bf16 v[110:113], v[212:215], v[172:175], v[110:113]
	v_mfma_f32_16x16x32_bf16 v[102:105], v[204:207], v[180:183], v[102:105]
	v_mfma_f32_16x16x32_bf16 v[94:97], v[212:215], v[180:183], v[94:97]
	v_mfma_f32_16x16x32_bf16 v[86:89], v[204:207], v[188:191], v[86:89]
	v_mfma_f32_16x16x32_bf16 v[78:81], v[212:215], v[188:191], v[78:81]
	v_mfma_f32_16x16x32_bf16 v[70:73], v[204:207], v[196:199], v[70:73]
	v_mfma_f32_16x16x32_bf16 v[66:69], v[212:215], v[196:199], v[66:69]
	s_barrier
	ds_read_b128 v[168:171], v149 offset:16384
	ds_read_b128 v[172:175], v149 offset:17408
	ds_read_b128 v[176:179], v149 offset:18432
	ds_read_b128 v[180:183], v149 offset:19456
	ds_read_b128 v[184:187], v149 offset:20480
	ds_read_b128 v[188:191], v149 offset:21504
	ds_read_b128 v[192:195], v149 offset:22528
	ds_read_b128 v[196:199], v149 offset:23552
	s_add_i32 s28, s74, s67
	v_lshl_add_u64 v[144:145], s[52:53], 0, v[134:135]
	s_mov_b32 m0, s28
	s_nop 0
	global_load_lds_dwordx4 v[144:145], off
	v_lshl_add_u64 v[216:217], s[52:53], 0, v[130:131]
	s_add_i32 m0, s28, 0x2000
	s_nop 0
	global_load_lds_dwordx4 v[216:217], off
	s_mov_b32 m0, s49
	v_lshl_add_u64 v[218:219], s[54:55], 0, v[136:137]
	global_load_lds_dwordx4 v[218:219], off
	v_lshl_add_u64 v[220:221], s[54:55], 0, v[132:133]
	s_mov_b32 m0, s68
	s_nop 0
	global_load_lds_dwordx4 v[220:221], off
	s_add_u32 s28, s52, 0x100000
	s_addc_u32 s29, s53, 0
	s_add_i32 s82, s75, s67
	v_lshl_add_u64 v[226:227], s[28:29], 0, v[134:135]
	s_mov_b32 m0, s82
	s_nop 0
	global_load_lds_dwordx4 v[226:227], off
	v_lshl_add_u64 v[226:227], s[28:29], 0, v[130:131]
	s_add_i32 m0, s82, 0x2000
	s_nop 0
	global_load_lds_dwordx4 v[226:227], off
	s_waitcnt vmcnt(8)
	s_waitcnt lgkmcnt(0)
	s_barrier
	v_mfma_f32_16x16x32_bf16 v[62:65], v[152:155], v[168:171], v[62:65]
	v_mfma_f32_16x16x32_bf16 v[58:61], v[160:163], v[168:171], v[58:61]
	v_mfma_f32_16x16x32_bf16 v[54:57], v[152:155], v[176:179], v[54:57]
	v_mfma_f32_16x16x32_bf16 v[46:49], v[160:163], v[176:179], v[46:49]
	v_mfma_f32_16x16x32_bf16 v[38:41], v[152:155], v[184:187], v[38:41]
	v_mfma_f32_16x16x32_bf16 v[30:33], v[160:163], v[184:187], v[30:33]
	v_mfma_f32_16x16x32_bf16 v[22:25], v[152:155], v[192:195], v[22:25]
	v_mfma_f32_16x16x32_bf16 v[14:17], v[160:163], v[192:195], v[14:17]
	v_mfma_f32_16x16x32_bf16 v[62:65], v[156:159], v[172:175], v[62:65]
	v_mfma_f32_16x16x32_bf16 v[58:61], v[164:167], v[172:175], v[58:61]
	v_mfma_f32_16x16x32_bf16 v[54:57], v[156:159], v[180:183], v[54:57]
	v_mfma_f32_16x16x32_bf16 v[46:49], v[164:167], v[180:183], v[46:49]
	v_mfma_f32_16x16x32_bf16 v[38:41], v[156:159], v[188:191], v[38:41]
	v_mfma_f32_16x16x32_bf16 v[30:33], v[164:167], v[188:191], v[30:33]
	v_mfma_f32_16x16x32_bf16 v[22:25], v[156:159], v[196:199], v[22:25]
	v_mfma_f32_16x16x32_bf16 v[14:17], v[164:167], v[196:199], v[14:17]
	v_mfma_f32_16x16x32_bf16 v[50:53], v[200:203], v[168:171], v[50:53]
	v_mfma_f32_16x16x32_bf16 v[42:45], v[208:211], v[168:171], v[42:45]
	v_mfma_f32_16x16x32_bf16 v[34:37], v[200:203], v[176:179], v[34:37]
	v_mfma_f32_16x16x32_bf16 v[26:29], v[208:211], v[176:179], v[26:29]
	v_mfma_f32_16x16x32_bf16 v[18:21], v[200:203], v[184:187], v[18:21]
	v_mfma_f32_16x16x32_bf16 v[10:13], v[208:211], v[184:187], v[10:13]
	v_mfma_f32_16x16x32_bf16 v[6:9], v[200:203], v[192:195], v[6:9]
	v_mfma_f32_16x16x32_bf16 v[2:5], v[208:211], v[192:195], v[2:5]
	v_mfma_f32_16x16x32_bf16 v[50:53], v[204:207], v[172:175], v[50:53]
	v_mfma_f32_16x16x32_bf16 v[42:45], v[212:215], v[172:175], v[42:45]
	v_mfma_f32_16x16x32_bf16 v[34:37], v[204:207], v[180:183], v[34:37]
	v_mfma_f32_16x16x32_bf16 v[26:29], v[212:215], v[180:183], v[26:29]
	v_mfma_f32_16x16x32_bf16 v[18:21], v[204:207], v[188:191], v[18:21]
	v_mfma_f32_16x16x32_bf16 v[10:13], v[212:215], v[188:191], v[10:13]
	v_mfma_f32_16x16x32_bf16 v[6:9], v[204:207], v[196:199], v[6:9]
	v_mfma_f32_16x16x32_bf16 v[2:5], v[212:215], v[196:199], v[2:5]
	s_add_i32 s82, 0, 0x18000
	v_add_u32_e32 v151, s82, v146
	s_barrier
	ds_read_b128 v[152:155], v151
	ds_read_b128 v[156:159], v151 offset:1024
	ds_read_b128 v[160:163], v151 offset:2048
	ds_read_b128 v[164:167], v151 offset:3072
	ds_read_b128 v[200:203], v151 offset:16384
	ds_read_b128 v[204:207], v151 offset:17408
	ds_read_b128 v[208:211], v151 offset:18432
	ds_read_b128 v[212:215], v151 offset:19456
	s_add_u32 s28, s54, 0x100000
	s_addc_u32 s29, s55, 0
	s_mov_b32 m0, s69
	v_lshl_add_u64 v[226:227], s[28:29], 0, v[136:137]
	ds_read_b128 v[168:171], v149 offset:32768
	ds_read_b128 v[172:175], v149 offset:33792
	ds_read_b128 v[176:179], v149 offset:34816
	ds_read_b128 v[180:183], v149 offset:35840
	ds_read_b128 v[184:187], v149 offset:36864
	ds_read_b128 v[188:191], v149 offset:37888
	ds_read_b128 v[192:195], v149 offset:38912
	ds_read_b128 v[196:199], v149 offset:39936
	global_load_lds_dwordx4 v[226:227], off
	v_lshl_add_u64 v[226:227], s[28:29], 0, v[132:133]
	s_mov_b32 m0, s70
	s_nop 0
	global_load_lds_dwordx4 v[226:227], off
	s_waitcnt vmcnt(8)
	s_waitcnt lgkmcnt(0)
	s_barrier
	v_mfma_f32_16x16x32_bf16 v[126:129], v[152:155], v[168:171], v[126:129]
	v_mfma_f32_16x16x32_bf16 v[122:125], v[160:163], v[168:171], v[122:125]
	v_mfma_f32_16x16x32_bf16 v[114:117], v[152:155], v[176:179], v[114:117]
	v_mfma_f32_16x16x32_bf16 v[106:109], v[160:163], v[176:179], v[106:109]
	v_mfma_f32_16x16x32_bf16 v[98:101], v[152:155], v[184:187], v[98:101]
	v_mfma_f32_16x16x32_bf16 v[90:93], v[160:163], v[184:187], v[90:93]
	v_mfma_f32_16x16x32_bf16 v[82:85], v[152:155], v[192:195], v[82:85]
	v_mfma_f32_16x16x32_bf16 v[74:77], v[160:163], v[192:195], v[74:77]
	v_mfma_f32_16x16x32_bf16 v[126:129], v[156:159], v[172:175], v[126:129]
	v_mfma_f32_16x16x32_bf16 v[122:125], v[164:167], v[172:175], v[122:125]
	v_mfma_f32_16x16x32_bf16 v[114:117], v[156:159], v[180:183], v[114:117]
	v_mfma_f32_16x16x32_bf16 v[106:109], v[164:167], v[180:183], v[106:109]
	v_mfma_f32_16x16x32_bf16 v[98:101], v[156:159], v[188:191], v[98:101]
	v_mfma_f32_16x16x32_bf16 v[90:93], v[164:167], v[188:191], v[90:93]
	v_mfma_f32_16x16x32_bf16 v[82:85], v[156:159], v[196:199], v[82:85]
	v_mfma_f32_16x16x32_bf16 v[74:77], v[164:167], v[196:199], v[74:77]
	v_mfma_f32_16x16x32_bf16 v[118:121], v[200:203], v[168:171], v[118:121]
	v_mfma_f32_16x16x32_bf16 v[110:113], v[208:211], v[168:171], v[110:113]
	v_mfma_f32_16x16x32_bf16 v[102:105], v[200:203], v[176:179], v[102:105]
	v_mfma_f32_16x16x32_bf16 v[94:97], v[208:211], v[176:179], v[94:97]
	v_mfma_f32_16x16x32_bf16 v[86:89], v[200:203], v[184:187], v[86:89]
	v_mfma_f32_16x16x32_bf16 v[78:81], v[208:211], v[184:187], v[78:81]
	v_mfma_f32_16x16x32_bf16 v[70:73], v[200:203], v[192:195], v[70:73]
	v_mfma_f32_16x16x32_bf16 v[66:69], v[208:211], v[192:195], v[66:69]
	v_mfma_f32_16x16x32_bf16 v[118:121], v[204:207], v[172:175], v[118:121]
	v_mfma_f32_16x16x32_bf16 v[110:113], v[212:215], v[172:175], v[110:113]
	v_mfma_f32_16x16x32_bf16 v[102:105], v[204:207], v[180:183], v[102:105]
	v_mfma_f32_16x16x32_bf16 v[94:97], v[212:215], v[180:183], v[94:97]
	v_mfma_f32_16x16x32_bf16 v[86:89], v[204:207], v[188:191], v[86:89]
	v_mfma_f32_16x16x32_bf16 v[78:81], v[212:215], v[188:191], v[78:81]
	v_mfma_f32_16x16x32_bf16 v[70:73], v[204:207], v[196:199], v[70:73]
	v_mfma_f32_16x16x32_bf16 v[66:69], v[212:215], v[196:199], v[66:69]
	s_barrier
	ds_read_b128 v[168:171], v149 offset:49152
	ds_read_b128 v[172:175], v149 offset:50176
	ds_read_b128 v[176:179], v149 offset:51200
	ds_read_b128 v[180:183], v149 offset:52224
	ds_read_b128 v[184:187], v149 offset:53248
	ds_read_b128 v[188:191], v149 offset:54272
	ds_read_b128 v[192:195], v149 offset:55296
	ds_read_b128 v[196:199], v149 offset:56320
	s_add_i32 s54, 0, 0x1c000
	s_add_i32 s28, s82, s67
	v_lshl_add_u64 v[144:145], v[144:145], 0, s[22:23]
	s_mov_b32 m0, s28
	s_nop 0
	global_load_lds_dwordx4 v[144:145], off
	v_lshl_add_u64 v[144:145], v[216:217], 0, s[22:23]
	s_add_i32 m0, s28, 0x2000
	s_nop 0
	global_load_lds_dwordx4 v[144:145], off
	s_mov_b32 m0, s72
	v_lshl_add_u64 v[144:145], v[218:219], 0, s[22:23]
	global_load_lds_dwordx4 v[144:145], off
	v_lshl_add_u64 v[144:145], v[220:221], 0, s[22:23]
	s_mov_b32 m0, s73
	s_nop 0
	global_load_lds_dwordx4 v[144:145], off
	s_add_u32 s28, s52, 0x100080
	s_addc_u32 s29, s53, 0
	s_add_i32 s52, s54, s67
	v_lshl_add_u64 v[144:145], s[28:29], 0, v[134:135]
	s_mov_b32 m0, s52
	s_nop 0
	global_load_lds_dwordx4 v[144:145], off
	v_lshl_add_u64 v[144:145], s[28:29], 0, v[130:131]
	s_add_i32 m0, s52, 0x2000
	s_nop 0
	global_load_lds_dwordx4 v[144:145], off
	s_waitcnt vmcnt(8)
	s_waitcnt lgkmcnt(0)
	s_barrier
	v_mfma_f32_16x16x32_bf16 v[62:65], v[152:155], v[168:171], v[62:65]
	v_mfma_f32_16x16x32_bf16 v[58:61], v[160:163], v[168:171], v[58:61]
	v_mfma_f32_16x16x32_bf16 v[54:57], v[152:155], v[176:179], v[54:57]
	v_mfma_f32_16x16x32_bf16 v[46:49], v[160:163], v[176:179], v[46:49]
	v_mfma_f32_16x16x32_bf16 v[38:41], v[152:155], v[184:187], v[38:41]
	v_mfma_f32_16x16x32_bf16 v[30:33], v[160:163], v[184:187], v[30:33]
	v_mfma_f32_16x16x32_bf16 v[22:25], v[152:155], v[192:195], v[22:25]
	v_mfma_f32_16x16x32_bf16 v[14:17], v[160:163], v[192:195], v[14:17]
	v_mfma_f32_16x16x32_bf16 v[62:65], v[156:159], v[172:175], v[62:65]
	v_mfma_f32_16x16x32_bf16 v[58:61], v[164:167], v[172:175], v[58:61]
	v_mfma_f32_16x16x32_bf16 v[54:57], v[156:159], v[180:183], v[54:57]
	v_mfma_f32_16x16x32_bf16 v[46:49], v[164:167], v[180:183], v[46:49]
	v_mfma_f32_16x16x32_bf16 v[38:41], v[156:159], v[188:191], v[38:41]
	v_mfma_f32_16x16x32_bf16 v[30:33], v[164:167], v[188:191], v[30:33]
	v_mfma_f32_16x16x32_bf16 v[22:25], v[156:159], v[196:199], v[22:25]
	v_mfma_f32_16x16x32_bf16 v[14:17], v[164:167], v[196:199], v[14:17]
	v_mfma_f32_16x16x32_bf16 v[50:53], v[200:203], v[168:171], v[50:53]
	v_mfma_f32_16x16x32_bf16 v[42:45], v[208:211], v[168:171], v[42:45]
	v_mfma_f32_16x16x32_bf16 v[34:37], v[200:203], v[176:179], v[34:37]
	v_mfma_f32_16x16x32_bf16 v[26:29], v[208:211], v[176:179], v[26:29]
	v_mfma_f32_16x16x32_bf16 v[18:21], v[200:203], v[184:187], v[18:21]
	v_mfma_f32_16x16x32_bf16 v[10:13], v[208:211], v[184:187], v[10:13]
	v_mfma_f32_16x16x32_bf16 v[6:9], v[200:203], v[192:195], v[6:9]
	v_mfma_f32_16x16x32_bf16 v[2:5], v[208:211], v[192:195], v[2:5]
	v_mfma_f32_16x16x32_bf16 v[50:53], v[204:207], v[172:175], v[50:53]
	v_mfma_f32_16x16x32_bf16 v[42:45], v[212:215], v[172:175], v[42:45]
	v_mfma_f32_16x16x32_bf16 v[34:37], v[204:207], v[180:183], v[34:37]
	v_mfma_f32_16x16x32_bf16 v[26:29], v[212:215], v[180:183], v[26:29]
	v_mfma_f32_16x16x32_bf16 v[18:21], v[204:207], v[188:191], v[18:21]
	v_mfma_f32_16x16x32_bf16 v[10:13], v[212:215], v[188:191], v[10:13]
	v_mfma_f32_16x16x32_bf16 v[6:9], v[204:207], v[196:199], v[6:9]
	v_mfma_f32_16x16x32_bf16 v[2:5], v[212:215], v[196:199], v[2:5]
	s_add_i32 s81, s81, 2
	s_add_u32 s39, s39, 0x100
	s_addc_u32 s41, s41, 0
	s_add_u32 s50, s50, 0x100
	s_addc_u32 s51, s51, 0
	s_cmp_gt_u32 s81, 61
	s_barrier
	s_cbranch_scc0 .LBB0_2485
	s_setprio 0
	v_lshl_add_u32 v152, s48, 8, v1
	v_lshl_or_b32 v144, s80, 8, v147
	v_ashrrev_i32_e32 v153, 31, v152
	v_ashrrev_i32_e32 v145, 31, v144
	v_lshlrev_b64 v[154:155], 13, v[152:153]
	v_lshl_add_u64 v[154:155], s[18:19], 0, v[154:155]
	v_lshlrev_b64 v[156:157], 1, v[144:145]
	v_lshl_add_u64 v[144:145], v[154:155], 0, v[156:157]
	v_cvt_pk_bf16_f32 v126, v126, v127
	v_cvt_pk_bf16_f32 v127, v128, v129
	v_cvt_pk_bf16_f32 v128, v122, v123
	v_cvt_pk_bf16_f32 v129, v124, v125
	global_store_dwordx4 v[144:145], v[126:129], off
	v_cvt_pk_bf16_f32 v118, v118, v119
	v_cvt_pk_bf16_f32 v119, v120, v121
	v_cvt_pk_bf16_f32 v120, v110, v111
	v_or_b32_e32 v110, 16, v152
	v_ashrrev_i32_e32 v111, 31, v110
	v_lshlrev_b64 v[110:111], 13, v[110:111]
	v_lshl_add_u64 v[110:111], s[18:19], 0, v[110:111]
	v_cvt_pk_bf16_f32 v121, v112, v113
	global_store_dwordx4 v[144:145], v[118:121], off offset:256
	s_mov_b32 s48, s40
	s_mov_b32 s80, s38
	v_lshl_add_u64 v[118:119], v[110:111], 0, v[156:157]
	v_cvt_pk_bf16_f32 v110, v114, v115
	v_cvt_pk_bf16_f32 v111, v116, v117
	v_cvt_pk_bf16_f32 v112, v106, v107
	v_cvt_pk_bf16_f32 v113, v108, v109
	global_store_dwordx4 v[118:119], v[110:113], off
	v_cvt_pk_bf16_f32 v102, v102, v103
	v_cvt_pk_bf16_f32 v103, v104, v105
	v_cvt_pk_bf16_f32 v104, v94, v95
	v_or_b32_e32 v94, 32, v152
	v_ashrrev_i32_e32 v95, 31, v94
	v_lshlrev_b64 v[94:95], 13, v[94:95]
	v_lshl_add_u64 v[94:95], s[18:19], 0, v[94:95]
	v_cvt_pk_bf16_f32 v105, v96, v97
	global_store_dwordx4 v[118:119], v[102:105], off offset:256
	s_mov_b64 s[52:53], s[46:47]
	s_mov_b64 s[50:51], s[44:45]
	v_lshl_add_u64 v[102:103], v[94:95], 0, v[156:157]
	v_cvt_pk_bf16_f32 v94, v98, v99
	v_cvt_pk_bf16_f32 v95, v100, v101
	v_cvt_pk_bf16_f32 v96, v90, v91
	v_cvt_pk_bf16_f32 v97, v92, v93
	global_store_dwordx4 v[102:103], v[94:97], off
	v_cvt_pk_bf16_f32 v86, v86, v87
	v_cvt_pk_bf16_f32 v87, v88, v89
	v_cvt_pk_bf16_f32 v88, v78, v79
	v_or_b32_e32 v78, 48, v152
	v_ashrrev_i32_e32 v79, 31, v78
	v_lshlrev_b64 v[78:79], 13, v[78:79]
	v_lshl_add_u64 v[78:79], s[18:19], 0, v[78:79]
	v_cvt_pk_bf16_f32 v89, v80, v81
	global_store_dwordx4 v[102:103], v[86:89], off offset:256
	s_nop 1
	v_lshl_add_u64 v[86:87], v[78:79], 0, v[156:157]
	v_cvt_pk_bf16_f32 v78, v82, v83
	v_cvt_pk_bf16_f32 v79, v84, v85
	v_cvt_pk_bf16_f32 v80, v74, v75
	v_cvt_pk_bf16_f32 v81, v76, v77
	global_store_dwordx4 v[86:87], v[78:81], off
	v_cvt_pk_bf16_f32 v70, v70, v71
	v_cvt_pk_bf16_f32 v71, v72, v73
	v_cvt_pk_bf16_f32 v72, v66, v67
	v_cvt_pk_bf16_f32 v73, v68, v69
	global_store_dwordx4 v[86:87], v[70:73], off offset:256
	v_cvt_pk_bf16_f32 v62, v62, v63
	v_cvt_pk_bf16_f32 v63, v64, v65
	v_cvt_pk_bf16_f32 v64, v58, v59
	v_add_co_u32_e32 v58, vcc, s76, v144
	v_lshl_add_u64 v[66:67], v[144:145], 0, s[20:21]
	s_nop 0
	v_addc_co_u32_e32 v59, vcc, 0, v145, vcc
	v_cvt_pk_bf16_f32 v65, v60, v61
	global_store_dwordx4 v[58:59], v[62:65], off
	v_cvt_pk_bf16_f32 v50, v50, v51
	v_cvt_pk_bf16_f32 v51, v52, v53
	v_cvt_pk_bf16_f32 v52, v42, v43
	v_cvt_pk_bf16_f32 v53, v44, v45
	global_store_dwordx4 v[66:67], v[50:53], off offset:256
	v_cvt_pk_bf16_f32 v42, v54, v55
	v_cvt_pk_bf16_f32 v43, v56, v57
	v_cvt_pk_bf16_f32 v44, v46, v47
	v_add_co_u32_e32 v46, vcc, s77, v144
	s_nop 0
	v_lshl_add_u64 v[50:51], v[144:145], 0, s[26:27]
	v_addc_co_u32_e32 v47, vcc, 0, v145, vcc
	v_cvt_pk_bf16_f32 v45, v48, v49
	global_store_dwordx4 v[46:47], v[42:45], off
	v_cvt_pk_bf16_f32 v34, v34, v35
	v_cvt_pk_bf16_f32 v35, v36, v37
	v_cvt_pk_bf16_f32 v36, v26, v27
	v_cvt_pk_bf16_f32 v37, v28, v29
	global_store_dwordx4 v[50:51], v[34:37], off offset:256
	v_cvt_pk_bf16_f32 v26, v38, v39
	v_cvt_pk_bf16_f32 v27, v40, v41
	v_cvt_pk_bf16_f32 v28, v30, v31
	v_add_co_u32_e32 v30, vcc, s78, v144
	s_nop 0
	v_lshl_add_u64 v[34:35], v[144:145], 0, s[34:35]
	v_addc_co_u32_e32 v31, vcc, 0, v145, vcc
	v_cvt_pk_bf16_f32 v29, v32, v33
	global_store_dwordx4 v[30:31], v[26:29], off
	v_cvt_pk_bf16_f32 v18, v18, v19
	v_cvt_pk_bf16_f32 v19, v20, v21
	v_cvt_pk_bf16_f32 v20, v10, v11
	v_cvt_pk_bf16_f32 v21, v12, v13
	global_store_dwordx4 v[34:35], v[18:21], off offset:256
	v_cvt_pk_bf16_f32 v10, v22, v23
	v_cvt_pk_bf16_f32 v11, v24, v25
	v_cvt_pk_bf16_f32 v12, v14, v15
	v_add_co_u32_e32 v14, vcc, s79, v144
	s_nop 0
	v_lshl_add_u64 v[18:19], v[144:145], 0, s[36:37]
	v_addc_co_u32_e32 v15, vcc, 0, v145, vcc
	s_and_b64 vcc, exec, s[6:7]
	v_cvt_pk_bf16_f32 v13, v16, v17
	global_store_dwordx4 v[14:15], v[10:13], off
	v_cvt_pk_bf16_f32 v6, v6, v7
	v_cvt_pk_bf16_f32 v7, v8, v9
	v_cvt_pk_bf16_f32 v8, v2, v3
	v_cvt_pk_bf16_f32 v9, v4, v5
	global_store_dwordx4 v[18:19], v[6:9], off offset:256
	s_cbranch_vccz .LBB0_2478
	s_waitcnt vmcnt(0)
	s_cmpk_gt_u32 s66, 0xff
	s_cbranch_scc1 .LBB0_2489
	s_barrier

.LBB0_3047:
	s_add_u32 s21, s38, 0x100
	s_addc_u32 s71, s39, 0
	s_add_u32 s38, s40, 0x100080
	v_mov_b32_e32 v2, 0
	s_addc_u32 s39, s41, 0
	s_mov_b32 s72, -2
	v_mov_b32_e32 v3, v2
	v_mov_b32_e32 v4, v2
	v_mov_b32_e32 v5, v2
	v_mov_b32_e32 v6, v2
	v_mov_b32_e32 v7, v2
	v_mov_b32_e32 v8, v2
	v_mov_b32_e32 v9, v2
	v_mov_b32_e32 v10, v2
	v_mov_b32_e32 v11, v2
	v_mov_b32_e32 v12, v2
	v_mov_b32_e32 v13, v2
	v_mov_b32_e32 v18, v2
	v_mov_b32_e32 v19, v2
	v_mov_b32_e32 v20, v2
	v_mov_b32_e32 v21, v2
	v_mov_b32_e32 v26, v2
	v_mov_b32_e32 v27, v2
	v_mov_b32_e32 v28, v2
	v_mov_b32_e32 v29, v2
	v_mov_b32_e32 v34, v2
	v_mov_b32_e32 v35, v2
	v_mov_b32_e32 v36, v2
	v_mov_b32_e32 v37, v2
	v_mov_b32_e32 v42, v2
	v_mov_b32_e32 v43, v2
	v_mov_b32_e32 v44, v2
	v_mov_b32_e32 v45, v2
	v_mov_b32_e32 v50, v2
	v_mov_b32_e32 v51, v2
	v_mov_b32_e32 v52, v2
	v_mov_b32_e32 v53, v2
	v_mov_b32_e32 v14, v2
	v_mov_b32_e32 v15, v2
	v_mov_b32_e32 v16, v2
	v_mov_b32_e32 v17, v2
	v_mov_b32_e32 v22, v2
	v_mov_b32_e32 v23, v2
	v_mov_b32_e32 v24, v2
	v_mov_b32_e32 v25, v2
	v_mov_b32_e32 v30, v2
	v_mov_b32_e32 v31, v2
	v_mov_b32_e32 v32, v2
	v_mov_b32_e32 v33, v2
	v_mov_b32_e32 v38, v2
	v_mov_b32_e32 v39, v2
	v_mov_b32_e32 v40, v2
	v_mov_b32_e32 v41, v2
	v_mov_b32_e32 v46, v2
	v_mov_b32_e32 v47, v2
	v_mov_b32_e32 v48, v2
	v_mov_b32_e32 v49, v2
	v_mov_b32_e32 v54, v2
	v_mov_b32_e32 v55, v2
	v_mov_b32_e32 v56, v2
	v_mov_b32_e32 v57, v2
	v_mov_b32_e32 v58, v2
	v_mov_b32_e32 v59, v2
	v_mov_b32_e32 v60, v2
	v_mov_b32_e32 v61, v2
	v_mov_b32_e32 v62, v2
	v_mov_b32_e32 v63, v2
	v_mov_b32_e32 v64, v2
	v_mov_b32_e32 v65, v2
	v_mov_b32_e32 v66, v2
	v_mov_b32_e32 v67, v2
	v_mov_b32_e32 v68, v2
	v_mov_b32_e32 v69, v2
	v_mov_b32_e32 v70, v2
	v_mov_b32_e32 v71, v2
	v_mov_b32_e32 v72, v2
	v_mov_b32_e32 v73, v2
	v_mov_b32_e32 v74, v2
	v_mov_b32_e32 v75, v2
	v_mov_b32_e32 v76, v2
	v_mov_b32_e32 v77, v2
	v_mov_b32_e32 v82, v2
	v_mov_b32_e32 v83, v2
	v_mov_b32_e32 v84, v2
	v_mov_b32_e32 v85, v2
	v_mov_b32_e32 v90, v2
	v_mov_b32_e32 v91, v2
	v_mov_b32_e32 v92, v2
	v_mov_b32_e32 v93, v2
	v_mov_b32_e32 v98, v2
	v_mov_b32_e32 v99, v2
	v_mov_b32_e32 v100, v2
	v_mov_b32_e32 v101, v2
	v_mov_b32_e32 v106, v2
	v_mov_b32_e32 v107, v2
	v_mov_b32_e32 v108, v2
	v_mov_b32_e32 v109, v2
	v_mov_b32_e32 v114, v2
	v_mov_b32_e32 v115, v2
	v_mov_b32_e32 v116, v2
	v_mov_b32_e32 v117, v2
	v_mov_b32_e32 v78, v2
	v_mov_b32_e32 v79, v2
	v_mov_b32_e32 v80, v2
	v_mov_b32_e32 v81, v2
	v_mov_b32_e32 v86, v2
	v_mov_b32_e32 v87, v2
	v_mov_b32_e32 v88, v2
	v_mov_b32_e32 v89, v2
	v_mov_b32_e32 v94, v2
	v_mov_b32_e32 v95, v2
	v_mov_b32_e32 v96, v2
	v_mov_b32_e32 v97, v2
	v_mov_b32_e32 v102, v2
	v_mov_b32_e32 v103, v2
	v_mov_b32_e32 v104, v2
	v_mov_b32_e32 v105, v2
	v_mov_b32_e32 v110, v2
	v_mov_b32_e32 v111, v2
	v_mov_b32_e32 v112, v2
	v_mov_b32_e32 v113, v2
	v_mov_b32_e32 v118, v2
	v_mov_b32_e32 v119, v2
	v_mov_b32_e32 v120, v2
	v_mov_b32_e32 v121, v2
	v_mov_b32_e32 v122, v2
	v_mov_b32_e32 v123, v2
	v_mov_b32_e32 v124, v2
	v_mov_b32_e32 v125, v2
	v_mov_b32_e32 v126, v2
	v_mov_b32_e32 v127, v2
	v_mov_b32_e32 v128, v2
	v_mov_b32_e32 v129, v2
	v_readfirstlane_b32 s98, v0
	s_nop 3
	s_lshr_b32 s98, s98, 8
	s_and_b32 s98, s98, 1
	s_cmp_eq_u32 s98, 1
	s_cbranch_scc0 .Lprio_skip_3048
	s_setprio 1
.Lprio_skip_3048:
.LBB0_3048:
	ds_read_b128 v[154:157], v150
	ds_read_b128 v[158:161], v150 offset:1024
	ds_read_b128 v[162:165], v150 offset:2048
	ds_read_b128 v[166:169], v150 offset:3072
	ds_read_b128 v[202:205], v152
	ds_read_b128 v[206:209], v152 offset:1024
	ds_read_b128 v[210:213], v152 offset:2048
	ds_read_b128 v[214:217], v152 offset:3072
	s_add_u32 s28, s38, 0xfff00080
	s_addc_u32 s29, s39, -1
	s_cmp_eq_u32 s72, 60
	s_cselect_b32 s45, s37, s29
	s_cselect_b32 s44, s36, s28
	s_cselect_b32 s41, s35, s71
	s_cselect_b32 s40, s34, s21
	v_lshl_add_u64 v[146:147], s[38:39], 0, v[142:143]
	s_add_i32 m0, s23, 0xc000
	ds_read_b128 v[170:173], v151
	ds_read_b128 v[174:177], v151 offset:1024
	ds_read_b128 v[178:181], v151 offset:2048
	ds_read_b128 v[182:185], v151 offset:3072
	ds_read_b128 v[186:189], v151 offset:4096
	ds_read_b128 v[190:193], v151 offset:5120
	ds_read_b128 v[194:197], v151 offset:6144
	ds_read_b128 v[198:201], v151 offset:7168
	global_load_lds_dwordx4 v[146:147], off
	v_lshl_add_u64 v[146:147], s[38:39], 0, v[140:141]
	s_add_i32 m0, s23, 0xe000
	s_nop 0
	global_load_lds_dwordx4 v[146:147], off
	s_waitcnt vmcnt(8)
	s_waitcnt lgkmcnt(0)
	s_barrier
	v_mfma_f32_16x16x32_bf16 v[126:129], v[154:157], v[170:173], v[126:129]
	v_mfma_f32_16x16x32_bf16 v[122:125], v[162:165], v[170:173], v[122:125]
	v_mfma_f32_16x16x32_bf16 v[118:121], v[154:157], v[178:181], v[118:121]
	v_mfma_f32_16x16x32_bf16 v[110:113], v[162:165], v[178:181], v[110:113]
	v_mfma_f32_16x16x32_bf16 v[102:105], v[154:157], v[186:189], v[102:105]
	v_mfma_f32_16x16x32_bf16 v[94:97], v[162:165], v[186:189], v[94:97]
	v_mfma_f32_16x16x32_bf16 v[86:89], v[154:157], v[194:197], v[86:89]
	v_mfma_f32_16x16x32_bf16 v[78:81], v[162:165], v[194:197], v[78:81]
	v_mfma_f32_16x16x32_bf16 v[126:129], v[158:161], v[174:177], v[126:129]
	v_mfma_f32_16x16x32_bf16 v[122:125], v[166:169], v[174:177], v[122:125]
	v_mfma_f32_16x16x32_bf16 v[118:121], v[158:161], v[182:185], v[118:121]
	v_mfma_f32_16x16x32_bf16 v[110:113], v[166:169], v[182:185], v[110:113]
	v_mfma_f32_16x16x32_bf16 v[102:105], v[158:161], v[190:193], v[102:105]
	v_mfma_f32_16x16x32_bf16 v[94:97], v[166:169], v[190:193], v[94:97]
	v_mfma_f32_16x16x32_bf16 v[86:89], v[158:161], v[198:201], v[86:89]
	v_mfma_f32_16x16x32_bf16 v[78:81], v[166:169], v[198:201], v[78:81]
	v_mfma_f32_16x16x32_bf16 v[114:117], v[202:205], v[170:173], v[114:117]
	v_mfma_f32_16x16x32_bf16 v[106:109], v[210:213], v[170:173], v[106:109]
	v_mfma_f32_16x16x32_bf16 v[98:101], v[202:205], v[178:181], v[98:101]
	v_mfma_f32_16x16x32_bf16 v[90:93], v[210:213], v[178:181], v[90:93]
	v_mfma_f32_16x16x32_bf16 v[82:85], v[202:205], v[186:189], v[82:85]
	v_mfma_f32_16x16x32_bf16 v[74:77], v[210:213], v[186:189], v[74:77]
	v_mfma_f32_16x16x32_bf16 v[70:73], v[202:205], v[194:197], v[70:73]
	v_mfma_f32_16x16x32_bf16 v[66:69], v[210:213], v[194:197], v[66:69]
	v_mfma_f32_16x16x32_bf16 v[114:117], v[206:209], v[174:177], v[114:117]
	v_mfma_f32_16x16x32_bf16 v[106:109], v[214:217], v[174:177], v[106:109]
	v_mfma_f32_16x16x32_bf16 v[98:101], v[206:209], v[182:185], v[98:101]
	v_mfma_f32_16x16x32_bf16 v[90:93], v[214:217], v[182:185], v[90:93]
	v_mfma_f32_16x16x32_bf16 v[82:85], v[206:209], v[190:193], v[82:85]
	v_mfma_f32_16x16x32_bf16 v[74:77], v[214:217], v[190:193], v[74:77]
	v_mfma_f32_16x16x32_bf16 v[70:73], v[206:209], v[198:201], v[70:73]
	v_mfma_f32_16x16x32_bf16 v[66:69], v[214:217], v[198:201], v[66:69]
	s_barrier
	ds_read_b128 v[170:173], v151 offset:16384
	ds_read_b128 v[174:177], v151 offset:17408
	ds_read_b128 v[178:181], v151 offset:18432
	ds_read_b128 v[182:185], v151 offset:19456
	ds_read_b128 v[186:189], v151 offset:20480
	ds_read_b128 v[190:193], v151 offset:21504
	ds_read_b128 v[194:197], v151 offset:22528
	ds_read_b128 v[198:201], v151 offset:23552
	s_add_i32 s28, s64, s54
	v_lshl_add_u64 v[146:147], s[40:41], 0, v[134:135]
	s_mov_b32 m0, s28
	s_nop 0
	global_load_lds_dwordx4 v[146:147], off
	v_lshl_add_u64 v[218:219], s[40:41], 0, v[130:131]
	s_add_i32 m0, s28, 0x2000
	s_nop 0
	global_load_lds_dwordx4 v[218:219], off
	s_mov_b32 m0, s23
	v_lshl_add_u64 v[220:221], s[44:45], 0, v[136:137]
	global_load_lds_dwordx4 v[220:221], off
	v_lshl_add_u64 v[222:223], s[44:45], 0, v[132:133]
	s_mov_b32 m0, s27
	s_nop 0
	global_load_lds_dwordx4 v[222:223], off
	s_add_u32 s28, s40, 0x100000
	s_addc_u32 s29, s41, 0
	s_add_i32 s73, s65, s54
	v_lshl_add_u64 v[226:227], s[28:29], 0, v[134:135]
	s_mov_b32 m0, s73
	s_nop 0
	global_load_lds_dwordx4 v[226:227], off
	v_lshl_add_u64 v[226:227], s[28:29], 0, v[130:131]
	s_add_i32 m0, s73, 0x2000
	s_nop 0
	global_load_lds_dwordx4 v[226:227], off
	s_waitcnt vmcnt(8)
	s_waitcnt lgkmcnt(0)
	s_barrier
	v_mfma_f32_16x16x32_bf16 v[62:65], v[154:157], v[170:173], v[62:65]
	v_mfma_f32_16x16x32_bf16 v[58:61], v[162:165], v[170:173], v[58:61]
	v_mfma_f32_16x16x32_bf16 v[54:57], v[154:157], v[178:181], v[54:57]
	v_mfma_f32_16x16x32_bf16 v[46:49], v[162:165], v[178:181], v[46:49]
	v_mfma_f32_16x16x32_bf16 v[38:41], v[154:157], v[186:189], v[38:41]
	v_mfma_f32_16x16x32_bf16 v[30:33], v[162:165], v[186:189], v[30:33]
	v_mfma_f32_16x16x32_bf16 v[22:25], v[154:157], v[194:197], v[22:25]
	v_mfma_f32_16x16x32_bf16 v[14:17], v[162:165], v[194:197], v[14:17]
	v_mfma_f32_16x16x32_bf16 v[62:65], v[158:161], v[174:177], v[62:65]
	v_mfma_f32_16x16x32_bf16 v[58:61], v[166:169], v[174:177], v[58:61]
	v_mfma_f32_16x16x32_bf16 v[54:57], v[158:161], v[182:185], v[54:57]
	v_mfma_f32_16x16x32_bf16 v[46:49], v[166:169], v[182:185], v[46:49]
	v_mfma_f32_16x16x32_bf16 v[38:41], v[158:161], v[190:193], v[38:41]
	v_mfma_f32_16x16x32_bf16 v[30:33], v[166:169], v[190:193], v[30:33]
	v_mfma_f32_16x16x32_bf16 v[22:25], v[158:161], v[198:201], v[22:25]
	v_mfma_f32_16x16x32_bf16 v[14:17], v[166:169], v[198:201], v[14:17]
	v_mfma_f32_16x16x32_bf16 v[50:53], v[202:205], v[170:173], v[50:53]
	v_mfma_f32_16x16x32_bf16 v[42:45], v[210:213], v[170:173], v[42:45]
	v_mfma_f32_16x16x32_bf16 v[34:37], v[202:205], v[178:181], v[34:37]
	v_mfma_f32_16x16x32_bf16 v[26:29], v[210:213], v[178:181], v[26:29]
	v_mfma_f32_16x16x32_bf16 v[18:21], v[202:205], v[186:189], v[18:21]
	v_mfma_f32_16x16x32_bf16 v[10:13], v[210:213], v[186:189], v[10:13]
	v_mfma_f32_16x16x32_bf16 v[6:9], v[202:205], v[194:197], v[6:9]
	v_mfma_f32_16x16x32_bf16 v[2:5], v[210:213], v[194:197], v[2:5]
	v_mfma_f32_16x16x32_bf16 v[50:53], v[206:209], v[174:177], v[50:53]
	v_mfma_f32_16x16x32_bf16 v[42:45], v[214:217], v[174:177], v[42:45]
	v_mfma_f32_16x16x32_bf16 v[34:37], v[206:209], v[182:185], v[34:37]
	v_mfma_f32_16x16x32_bf16 v[26:29], v[214:217], v[182:185], v[26:29]
	v_mfma_f32_16x16x32_bf16 v[18:21], v[206:209], v[190:193], v[18:21]
	v_mfma_f32_16x16x32_bf16 v[10:13], v[214:217], v[190:193], v[10:13]
	v_mfma_f32_16x16x32_bf16 v[6:9], v[206:209], v[198:201], v[6:9]
	v_mfma_f32_16x16x32_bf16 v[2:5], v[214:217], v[198:201], v[2:5]
	s_add_i32 s73, 0, 0x18000
	v_add_u32_e32 v153, s73, v148
	s_barrier
	ds_read_b128 v[154:157], v153
	ds_read_b128 v[158:161], v153 offset:1024
	ds_read_b128 v[162:165], v153 offset:2048
	ds_read_b128 v[166:169], v153 offset:3072
	ds_read_b128 v[202:205], v153 offset:16384
	ds_read_b128 v[206:209], v153 offset:17408
	ds_read_b128 v[210:213], v153 offset:18432
	ds_read_b128 v[214:217], v153 offset:19456
	s_add_u32 s28, s44, 0x100000
	s_addc_u32 s29, s45, 0
	s_mov_b32 m0, s55
	v_lshl_add_u64 v[226:227], s[28:29], 0, v[136:137]
	ds_read_b128 v[170:173], v151 offset:32768
	ds_read_b128 v[174:177], v151 offset:33792
	ds_read_b128 v[178:181], v151 offset:34816
	ds_read_b128 v[182:185], v151 offset:35840
	ds_read_b128 v[186:189], v151 offset:36864
	ds_read_b128 v[190:193], v151 offset:37888
	ds_read_b128 v[194:197], v151 offset:38912
	ds_read_b128 v[198:201], v151 offset:39936
	global_load_lds_dwordx4 v[226:227], off
	v_lshl_add_u64 v[226:227], s[28:29], 0, v[132:133]
	s_mov_b32 m0, s56
	s_nop 0
	global_load_lds_dwordx4 v[226:227], off
	s_waitcnt vmcnt(8)
	s_waitcnt lgkmcnt(0)
	s_barrier
	v_mfma_f32_16x16x32_bf16 v[126:129], v[154:157], v[170:173], v[126:129]
	v_mfma_f32_16x16x32_bf16 v[122:125], v[162:165], v[170:173], v[122:125]
	v_mfma_f32_16x16x32_bf16 v[118:121], v[154:157], v[178:181], v[118:121]
	v_mfma_f32_16x16x32_bf16 v[110:113], v[162:165], v[178:181], v[110:113]
	v_mfma_f32_16x16x32_bf16 v[102:105], v[154:157], v[186:189], v[102:105]
	v_mfma_f32_16x16x32_bf16 v[94:97], v[162:165], v[186:189], v[94:97]
	v_mfma_f32_16x16x32_bf16 v[86:89], v[154:157], v[194:197], v[86:89]
	v_mfma_f32_16x16x32_bf16 v[78:81], v[162:165], v[194:197], v[78:81]
	v_mfma_f32_16x16x32_bf16 v[126:129], v[158:161], v[174:177], v[126:129]
	v_mfma_f32_16x16x32_bf16 v[122:125], v[166:169], v[174:177], v[122:125]
	v_mfma_f32_16x16x32_bf16 v[118:121], v[158:161], v[182:185], v[118:121]
	v_mfma_f32_16x16x32_bf16 v[110:113], v[166:169], v[182:185], v[110:113]
	v_mfma_f32_16x16x32_bf16 v[102:105], v[158:161], v[190:193], v[102:105]
	v_mfma_f32_16x16x32_bf16 v[94:97], v[166:169], v[190:193], v[94:97]
	v_mfma_f32_16x16x32_bf16 v[86:89], v[158:161], v[198:201], v[86:89]
	v_mfma_f32_16x16x32_bf16 v[78:81], v[166:169], v[198:201], v[78:81]
	v_mfma_f32_16x16x32_bf16 v[114:117], v[202:205], v[170:173], v[114:117]
	v_mfma_f32_16x16x32_bf16 v[106:109], v[210:213], v[170:173], v[106:109]
	v_mfma_f32_16x16x32_bf16 v[98:101], v[202:205], v[178:181], v[98:101]
	v_mfma_f32_16x16x32_bf16 v[90:93], v[210:213], v[178:181], v[90:93]
	v_mfma_f32_16x16x32_bf16 v[82:85], v[202:205], v[186:189], v[82:85]
	v_mfma_f32_16x16x32_bf16 v[74:77], v[210:213], v[186:189], v[74:77]
	v_mfma_f32_16x16x32_bf16 v[70:73], v[202:205], v[194:197], v[70:73]
	v_mfma_f32_16x16x32_bf16 v[66:69], v[210:213], v[194:197], v[66:69]
	v_mfma_f32_16x16x32_bf16 v[114:117], v[206:209], v[174:177], v[114:117]
	v_mfma_f32_16x16x32_bf16 v[106:109], v[214:217], v[174:177], v[106:109]
	v_mfma_f32_16x16x32_bf16 v[98:101], v[206:209], v[182:185], v[98:101]
	v_mfma_f32_16x16x32_bf16 v[90:93], v[214:217], v[182:185], v[90:93]
	v_mfma_f32_16x16x32_bf16 v[82:85], v[206:209], v[190:193], v[82:85]
	v_mfma_f32_16x16x32_bf16 v[74:77], v[214:217], v[190:193], v[74:77]
	v_mfma_f32_16x16x32_bf16 v[70:73], v[206:209], v[198:201], v[70:73]
	v_mfma_f32_16x16x32_bf16 v[66:69], v[214:217], v[198:201], v[66:69]
	s_barrier
	ds_read_b128 v[170:173], v151 offset:49152
	ds_read_b128 v[174:177], v151 offset:50176
	ds_read_b128 v[178:181], v151 offset:51200
	ds_read_b128 v[182:185], v151 offset:52224
	ds_read_b128 v[186:189], v151 offset:53248
	ds_read_b128 v[190:193], v151 offset:54272
	ds_read_b128 v[194:197], v151 offset:55296
	ds_read_b128 v[198:201], v151 offset:56320
	s_add_i32 s44, 0, 0x1c000
	s_add_i32 s28, s73, s54
	v_lshl_add_u64 v[146:147], v[146:147], 0, s[6:7]
	s_mov_b32 m0, s28
	s_nop 0
	global_load_lds_dwordx4 v[146:147], off
	v_lshl_add_u64 v[146:147], v[218:219], 0, s[6:7]
	s_add_i32 m0, s28, 0x2000
	s_nop 0
	global_load_lds_dwordx4 v[146:147], off
	s_mov_b32 m0, s59
	v_lshl_add_u64 v[146:147], v[220:221], 0, s[6:7]
	global_load_lds_dwordx4 v[146:147], off
	v_lshl_add_u64 v[146:147], v[222:223], 0, s[6:7]
	s_mov_b32 m0, s60
	s_nop 0
	global_load_lds_dwordx4 v[146:147], off
	s_add_u32 s28, s40, 0x100080
	s_addc_u32 s29, s41, 0
	s_add_i32 s40, s44, s54
	v_lshl_add_u64 v[146:147], s[28:29], 0, v[134:135]
	s_mov_b32 m0, s40
	s_nop 0
	global_load_lds_dwordx4 v[146:147], off
	v_lshl_add_u64 v[146:147], s[28:29], 0, v[130:131]
	s_add_i32 m0, s40, 0x2000
	s_nop 0
	global_load_lds_dwordx4 v[146:147], off
	s_waitcnt vmcnt(8)
	s_waitcnt lgkmcnt(0)
	s_barrier
	v_mfma_f32_16x16x32_bf16 v[62:65], v[154:157], v[170:173], v[62:65]
	v_mfma_f32_16x16x32_bf16 v[58:61], v[162:165], v[170:173], v[58:61]
	v_mfma_f32_16x16x32_bf16 v[54:57], v[154:157], v[178:181], v[54:57]
	v_mfma_f32_16x16x32_bf16 v[46:49], v[162:165], v[178:181], v[46:49]
	v_mfma_f32_16x16x32_bf16 v[38:41], v[154:157], v[186:189], v[38:41]
	v_mfma_f32_16x16x32_bf16 v[30:33], v[162:165], v[186:189], v[30:33]
	v_mfma_f32_16x16x32_bf16 v[22:25], v[154:157], v[194:197], v[22:25]
	v_mfma_f32_16x16x32_bf16 v[14:17], v[162:165], v[194:197], v[14:17]
	v_mfma_f32_16x16x32_bf16 v[62:65], v[158:161], v[174:177], v[62:65]
	v_mfma_f32_16x16x32_bf16 v[58:61], v[166:169], v[174:177], v[58:61]
	v_mfma_f32_16x16x32_bf16 v[54:57], v[158:161], v[182:185], v[54:57]
	v_mfma_f32_16x16x32_bf16 v[46:49], v[166:169], v[182:185], v[46:49]
	v_mfma_f32_16x16x32_bf16 v[38:41], v[158:161], v[190:193], v[38:41]
	v_mfma_f32_16x16x32_bf16 v[30:33], v[166:169], v[190:193], v[30:33]
	v_mfma_f32_16x16x32_bf16 v[22:25], v[158:161], v[198:201], v[22:25]
	v_mfma_f32_16x16x32_bf16 v[14:17], v[166:169], v[198:201], v[14:17]
	v_mfma_f32_16x16x32_bf16 v[50:53], v[202:205], v[170:173], v[50:53]
	v_mfma_f32_16x16x32_bf16 v[42:45], v[210:213], v[170:173], v[42:45]
	v_mfma_f32_16x16x32_bf16 v[34:37], v[202:205], v[178:181], v[34:37]
	v_mfma_f32_16x16x32_bf16 v[26:29], v[210:213], v[178:181], v[26:29]
	v_mfma_f32_16x16x32_bf16 v[18:21], v[202:205], v[186:189], v[18:21]
	v_mfma_f32_16x16x32_bf16 v[10:13], v[210:213], v[186:189], v[10:13]
	v_mfma_f32_16x16x32_bf16 v[6:9], v[202:205], v[194:197], v[6:9]
	v_mfma_f32_16x16x32_bf16 v[2:5], v[210:213], v[194:197], v[2:5]
	v_mfma_f32_16x16x32_bf16 v[50:53], v[206:209], v[174:177], v[50:53]
	v_mfma_f32_16x16x32_bf16 v[42:45], v[214:217], v[174:177], v[42:45]
	v_mfma_f32_16x16x32_bf16 v[34:37], v[206:209], v[182:185], v[34:37]
	v_mfma_f32_16x16x32_bf16 v[26:29], v[214:217], v[182:185], v[26:29]
	v_mfma_f32_16x16x32_bf16 v[18:21], v[206:209], v[190:193], v[18:21]
	v_mfma_f32_16x16x32_bf16 v[10:13], v[214:217], v[190:193], v[10:13]
	v_mfma_f32_16x16x32_bf16 v[6:9], v[206:209], v[198:201], v[6:9]
	v_mfma_f32_16x16x32_bf16 v[2:5], v[214:217], v[198:201], v[2:5]
	s_add_i32 s72, s72, 2
	s_add_u32 s21, s21, 0x100
	s_addc_u32 s71, s71, 0
	s_add_u32 s38, s38, 0x100
	s_addc_u32 s39, s39, 0
	s_cmp_gt_u32 s72, 61
	s_barrier
	s_cbranch_scc0 .LBB0_3048
	s_setprio 0
	s_cmp_lt_i32 s70, 2
	s_cbranch_scc1 .LBB0_3053
	s_cmp_eq_u32 s70, 2
	s_mov_b64 s[38:39], -1
	s_cbranch_scc0 .LBB0_3052
	v_lshl_add_u32 v146, s26, 8, v1
	v_or_b32_e32 v156, 16, v146
	v_ashrrev_i32_e32 v147, 31, v146
	v_ashrrev_i32_e32 v157, 31, v156
	v_lshlrev_b64 v[154:155], 10, v[146:147]
	v_lshlrev_b64 v[156:157], 10, v[156:157]
	v_lshl_add_u64 v[154:155], v[138:139], 0, v[154:155]
	v_lshl_add_u64 v[156:157], v[138:139], 0, v[156:157]
	global_store_dwordx4 v[154:155], v[126:129], off
	global_store_dwordx4 v[154:155], v[122:125], off offset:16
	global_store_dwordx4 v[154:155], v[114:117], off offset:512
	global_store_dwordx4 v[154:155], v[106:109], off offset:528
	global_store_dwordx4 v[156:157], v[118:121], off
	global_store_dwordx4 v[156:157], v[110:113], off offset:16
	global_store_dwordx4 v[156:157], v[98:101], off offset:512
	global_store_dwordx4 v[156:157], v[90:93], off offset:528
	v_or_b32_e32 v156, 32, v146
	v_ashrrev_i32_e32 v157, 31, v156
	v_lshlrev_b64 v[156:157], 10, v[156:157]
	v_or_b32_e32 v146, 48, v146
	v_lshl_add_u64 v[156:157], v[138:139], 0, v[156:157]
	v_ashrrev_i32_e32 v147, 31, v146
	global_store_dwordx4 v[156:157], v[102:105], off
	global_store_dwordx4 v[156:157], v[94:97], off offset:16
	global_store_dwordx4 v[156:157], v[82:85], off offset:512
	global_store_dwordx4 v[156:157], v[74:77], off offset:528
	v_lshlrev_b64 v[146:147], 10, v[146:147]
	v_add_co_u32_e32 v156, vcc, s66, v154
	v_lshl_add_u64 v[146:147], v[138:139], 0, v[146:147]
	s_nop 0
	v_addc_co_u32_e32 v157, vcc, 0, v155, vcc
	global_store_dwordx4 v[146:147], v[86:89], off
	global_store_dwordx4 v[146:147], v[78:81], off offset:16
	global_store_dwordx4 v[146:147], v[70:73], off offset:512
	global_store_dwordx4 v[146:147], v[66:69], off offset:528
	v_lshl_add_u64 v[146:147], v[154:155], 0, s[8:9]
	global_store_dwordx4 v[156:157], v[62:65], off
	global_store_dwordx4 v[146:147], v[58:61], off offset:16
	global_store_dwordx4 v[146:147], v[50:53], off offset:512
	global_store_dwordx4 v[146:147], v[42:45], off offset:528
	v_add_co_u32_e32 v156, vcc, s67, v154
	v_lshl_add_u64 v[146:147], v[154:155], 0, s[12:13]
	s_nop 0
	v_addc_co_u32_e32 v157, vcc, 0, v155, vcc
	global_store_dwordx4 v[156:157], v[54:57], off
	global_store_dwordx4 v[146:147], v[46:49], off offset:16
	global_store_dwordx4 v[146:147], v[34:37], off offset:512
	global_store_dwordx4 v[146:147], v[26:29], off offset:528
	v_add_co_u32_e32 v156, vcc, s68, v154
	v_lshl_add_u64 v[146:147], v[154:155], 0, s[14:15]
	s_nop 0
	v_addc_co_u32_e32 v157, vcc, 0, v155, vcc
	global_store_dwordx4 v[156:157], v[38:41], off
	global_store_dwordx4 v[146:147], v[30:33], off offset:16
	global_store_dwordx4 v[146:147], v[18:21], off offset:512
	global_store_dwordx4 v[146:147], v[10:13], off offset:528
	v_lshl_add_u64 v[146:147], v[154:155], 0, s[16:17]
	v_add_co_u32_e32 v154, vcc, 0x2c000, v154
	s_mov_b64 s[38:39], 0
	s_nop 0
	v_addc_co_u32_e32 v155, vcc, 0, v155, vcc
	global_store_dwordx4 v[154:155], v[22:25], off
	global_store_dwordx4 v[146:147], v[14:17], off offset:16
	global_store_dwordx4 v[146:147], v[6:9], off offset:512
	global_store_dwordx4 v[146:147], v[2:5], off offset:528

.LBB0_4132:
	s_add_u32 s21, s40, 0x100
	s_addc_u32 s23, s41, 0
	s_add_u32 s38, s38, 0x100080
	v_mov_b32_e32 v2, 0
	s_addc_u32 s39, s39, 0
	s_mov_b32 s60, -2
	v_mov_b32_e32 v3, v2
	v_mov_b32_e32 v4, v2
	v_mov_b32_e32 v5, v2
	v_mov_b32_e32 v6, v2
	v_mov_b32_e32 v7, v2
	v_mov_b32_e32 v8, v2
	v_mov_b32_e32 v9, v2
	v_mov_b32_e32 v10, v2
	v_mov_b32_e32 v11, v2
	v_mov_b32_e32 v12, v2
	v_mov_b32_e32 v13, v2
	v_mov_b32_e32 v18, v2
	v_mov_b32_e32 v19, v2
	v_mov_b32_e32 v20, v2
	v_mov_b32_e32 v21, v2
	v_mov_b32_e32 v26, v2
	v_mov_b32_e32 v27, v2
	v_mov_b32_e32 v28, v2
	v_mov_b32_e32 v29, v2
	v_mov_b32_e32 v34, v2
	v_mov_b32_e32 v35, v2
	v_mov_b32_e32 v36, v2
	v_mov_b32_e32 v37, v2
	v_mov_b32_e32 v42, v2
	v_mov_b32_e32 v43, v2
	v_mov_b32_e32 v44, v2
	v_mov_b32_e32 v45, v2
	v_mov_b32_e32 v50, v2
	v_mov_b32_e32 v51, v2
	v_mov_b32_e32 v52, v2
	v_mov_b32_e32 v53, v2
	v_mov_b32_e32 v14, v2
	v_mov_b32_e32 v15, v2
	v_mov_b32_e32 v16, v2
	v_mov_b32_e32 v17, v2
	v_mov_b32_e32 v22, v2
	v_mov_b32_e32 v23, v2
	v_mov_b32_e32 v24, v2
	v_mov_b32_e32 v25, v2
	v_mov_b32_e32 v30, v2
	v_mov_b32_e32 v31, v2
	v_mov_b32_e32 v32, v2
	v_mov_b32_e32 v33, v2
	v_mov_b32_e32 v38, v2
	v_mov_b32_e32 v39, v2
	v_mov_b32_e32 v40, v2
	v_mov_b32_e32 v41, v2
	v_mov_b32_e32 v46, v2
	v_mov_b32_e32 v47, v2
	v_mov_b32_e32 v48, v2
	v_mov_b32_e32 v49, v2
	v_mov_b32_e32 v54, v2
	v_mov_b32_e32 v55, v2
	v_mov_b32_e32 v56, v2
	v_mov_b32_e32 v57, v2
	v_mov_b32_e32 v58, v2
	v_mov_b32_e32 v59, v2
	v_mov_b32_e32 v60, v2
	v_mov_b32_e32 v61, v2
	v_mov_b32_e32 v62, v2
	v_mov_b32_e32 v63, v2
	v_mov_b32_e32 v64, v2
	v_mov_b32_e32 v65, v2
	v_mov_b32_e32 v66, v2
	v_mov_b32_e32 v67, v2
	v_mov_b32_e32 v68, v2
	v_mov_b32_e32 v69, v2
	v_mov_b32_e32 v70, v2
	v_mov_b32_e32 v71, v2
	v_mov_b32_e32 v72, v2
	v_mov_b32_e32 v73, v2
	v_mov_b32_e32 v78, v2
	v_mov_b32_e32 v79, v2
	v_mov_b32_e32 v80, v2
	v_mov_b32_e32 v81, v2
	v_mov_b32_e32 v86, v2
	v_mov_b32_e32 v87, v2
	v_mov_b32_e32 v88, v2
	v_mov_b32_e32 v89, v2
	v_mov_b32_e32 v94, v2
	v_mov_b32_e32 v95, v2
	v_mov_b32_e32 v96, v2
	v_mov_b32_e32 v97, v2
	v_mov_b32_e32 v102, v2
	v_mov_b32_e32 v103, v2
	v_mov_b32_e32 v104, v2
	v_mov_b32_e32 v105, v2
	v_mov_b32_e32 v110, v2
	v_mov_b32_e32 v111, v2
	v_mov_b32_e32 v112, v2
	v_mov_b32_e32 v113, v2
	v_mov_b32_e32 v118, v2
	v_mov_b32_e32 v119, v2
	v_mov_b32_e32 v120, v2
	v_mov_b32_e32 v121, v2
	v_mov_b32_e32 v74, v2
	v_mov_b32_e32 v75, v2
	v_mov_b32_e32 v76, v2
	v_mov_b32_e32 v77, v2
	v_mov_b32_e32 v82, v2
	v_mov_b32_e32 v83, v2
	v_mov_b32_e32 v84, v2
	v_mov_b32_e32 v85, v2
	v_mov_b32_e32 v90, v2
	v_mov_b32_e32 v91, v2
	v_mov_b32_e32 v92, v2
	v_mov_b32_e32 v93, v2
	v_mov_b32_e32 v98, v2
	v_mov_b32_e32 v99, v2
	v_mov_b32_e32 v100, v2
	v_mov_b32_e32 v101, v2
	v_mov_b32_e32 v106, v2
	v_mov_b32_e32 v107, v2
	v_mov_b32_e32 v108, v2
	v_mov_b32_e32 v109, v2
	v_mov_b32_e32 v114, v2
	v_mov_b32_e32 v115, v2
	v_mov_b32_e32 v116, v2
	v_mov_b32_e32 v117, v2
	v_mov_b32_e32 v122, v2
	v_mov_b32_e32 v123, v2
	v_mov_b32_e32 v124, v2
	v_mov_b32_e32 v125, v2
	v_mov_b32_e32 v126, v2
	v_mov_b32_e32 v127, v2
	v_mov_b32_e32 v128, v2
	v_mov_b32_e32 v129, v2
	v_readfirstlane_b32 s98, v0
	s_nop 3
	s_lshr_b32 s98, s98, 8
	s_and_b32 s98, s98, 1
	s_cmp_eq_u32 s98, 1
	s_cbranch_scc0 .Lprio_skip_4133
	s_setprio 1
.Lprio_skip_4133:
.LBB0_4133:
	ds_read_b128 v[152:155], v148
	ds_read_b128 v[156:159], v148 offset:1024
	ds_read_b128 v[160:163], v148 offset:2048
	ds_read_b128 v[164:167], v148 offset:3072
	ds_read_b128 v[200:203], v150
	ds_read_b128 v[204:207], v150 offset:1024
	ds_read_b128 v[208:211], v150 offset:2048
	ds_read_b128 v[212:215], v150 offset:3072
	s_add_u32 s28, s38, 0xfff00080
	s_addc_u32 s29, s39, -1
	s_cmp_eq_u32 s60, 60
	s_cselect_b32 s45, s27, s29
	s_cselect_b32 s44, s26, s28
	s_cselect_b32 s41, s35, s23
	s_cselect_b32 s40, s34, s21
	v_lshl_add_u64 v[144:145], s[38:39], 0, v[140:141]
	s_add_i32 m0, s37, 0xc000
	ds_read_b128 v[168:171], v149
	ds_read_b128 v[172:175], v149 offset:1024
	ds_read_b128 v[176:179], v149 offset:2048
	ds_read_b128 v[180:183], v149 offset:3072
	ds_read_b128 v[184:187], v149 offset:4096
	ds_read_b128 v[188:191], v149 offset:5120
	ds_read_b128 v[192:195], v149 offset:6144
	ds_read_b128 v[196:199], v149 offset:7168
	global_load_lds_dwordx4 v[144:145], off
	v_lshl_add_u64 v[144:145], s[38:39], 0, v[138:139]
	s_add_i32 m0, s37, 0xe000
	s_nop 0
	global_load_lds_dwordx4 v[144:145], off
	s_waitcnt vmcnt(8)
	s_waitcnt lgkmcnt(0)
	s_barrier
	v_mfma_f32_16x16x32_bf16 v[126:129], v[152:155], v[168:171], v[126:129]
	v_mfma_f32_16x16x32_bf16 v[122:125], v[160:163], v[168:171], v[122:125]
	v_mfma_f32_16x16x32_bf16 v[114:117], v[152:155], v[176:179], v[114:117]
	v_mfma_f32_16x16x32_bf16 v[106:109], v[160:163], v[176:179], v[106:109]
	v_mfma_f32_16x16x32_bf16 v[98:101], v[152:155], v[184:187], v[98:101]
	v_mfma_f32_16x16x32_bf16 v[90:93], v[160:163], v[184:187], v[90:93]
	v_mfma_f32_16x16x32_bf16 v[82:85], v[152:155], v[192:195], v[82:85]
	v_mfma_f32_16x16x32_bf16 v[74:77], v[160:163], v[192:195], v[74:77]
	v_mfma_f32_16x16x32_bf16 v[126:129], v[156:159], v[172:175], v[126:129]
	v_mfma_f32_16x16x32_bf16 v[122:125], v[164:167], v[172:175], v[122:125]
	v_mfma_f32_16x16x32_bf16 v[114:117], v[156:159], v[180:183], v[114:117]
	v_mfma_f32_16x16x32_bf16 v[106:109], v[164:167], v[180:183], v[106:109]
	v_mfma_f32_16x16x32_bf16 v[98:101], v[156:159], v[188:191], v[98:101]
	v_mfma_f32_16x16x32_bf16 v[90:93], v[164:167], v[188:191], v[90:93]
	v_mfma_f32_16x16x32_bf16 v[82:85], v[156:159], v[196:199], v[82:85]
	v_mfma_f32_16x16x32_bf16 v[74:77], v[164:167], v[196:199], v[74:77]
	v_mfma_f32_16x16x32_bf16 v[118:121], v[200:203], v[168:171], v[118:121]
	v_mfma_f32_16x16x32_bf16 v[110:113], v[208:211], v[168:171], v[110:113]
	v_mfma_f32_16x16x32_bf16 v[102:105], v[200:203], v[176:179], v[102:105]
	v_mfma_f32_16x16x32_bf16 v[94:97], v[208:211], v[176:179], v[94:97]
	v_mfma_f32_16x16x32_bf16 v[86:89], v[200:203], v[184:187], v[86:89]
	v_mfma_f32_16x16x32_bf16 v[78:81], v[208:211], v[184:187], v[78:81]
	v_mfma_f32_16x16x32_bf16 v[70:73], v[200:203], v[192:195], v[70:73]
	v_mfma_f32_16x16x32_bf16 v[66:69], v[208:211], v[192:195], v[66:69]
	v_mfma_f32_16x16x32_bf16 v[118:121], v[204:207], v[172:175], v[118:121]
	v_mfma_f32_16x16x32_bf16 v[110:113], v[212:215], v[172:175], v[110:113]
	v_mfma_f32_16x16x32_bf16 v[102:105], v[204:207], v[180:183], v[102:105]
	v_mfma_f32_16x16x32_bf16 v[94:97], v[212:215], v[180:183], v[94:97]
	v_mfma_f32_16x16x32_bf16 v[86:89], v[204:207], v[188:191], v[86:89]
	v_mfma_f32_16x16x32_bf16 v[78:81], v[212:215], v[188:191], v[78:81]
	v_mfma_f32_16x16x32_bf16 v[70:73], v[204:207], v[196:199], v[70:73]
	v_mfma_f32_16x16x32_bf16 v[66:69], v[212:215], v[196:199], v[66:69]
	s_barrier
	ds_read_b128 v[168:171], v149 offset:16384
	ds_read_b128 v[172:175], v149 offset:17408
	ds_read_b128 v[176:179], v149 offset:18432
	ds_read_b128 v[180:183], v149 offset:19456
	ds_read_b128 v[184:187], v149 offset:20480
	ds_read_b128 v[188:191], v149 offset:21504
	ds_read_b128 v[192:195], v149 offset:22528
	ds_read_b128 v[196:199], v149 offset:23552
	s_add_i32 s28, s53, s31
	v_lshl_add_u64 v[144:145], s[40:41], 0, v[134:135]
	s_mov_b32 m0, s28
	s_nop 0
	global_load_lds_dwordx4 v[144:145], off
	v_lshl_add_u64 v[216:217], s[40:41], 0, v[130:131]
	s_add_i32 m0, s28, 0x2000
	s_nop 0
	global_load_lds_dwordx4 v[216:217], off
	s_mov_b32 m0, s37
	v_lshl_add_u64 v[218:219], s[44:45], 0, v[136:137]
	global_load_lds_dwordx4 v[218:219], off
	v_lshl_add_u64 v[220:221], s[44:45], 0, v[132:133]
	s_mov_b32 m0, s46
	s_nop 0
	global_load_lds_dwordx4 v[220:221], off
	s_add_u32 s28, s40, 0x100000
	s_addc_u32 s29, s41, 0
	s_add_i32 s61, s54, s31
	v_lshl_add_u64 v[226:227], s[28:29], 0, v[134:135]
	s_mov_b32 m0, s61
	s_nop 0
	global_load_lds_dwordx4 v[226:227], off
	v_lshl_add_u64 v[226:227], s[28:29], 0, v[130:131]
	s_add_i32 m0, s61, 0x2000
	s_nop 0
	global_load_lds_dwordx4 v[226:227], off
	s_waitcnt vmcnt(8)
	s_waitcnt lgkmcnt(0)
	s_barrier
	v_mfma_f32_16x16x32_bf16 v[62:65], v[152:155], v[168:171], v[62:65]
	v_mfma_f32_16x16x32_bf16 v[58:61], v[160:163], v[168:171], v[58:61]
	v_mfma_f32_16x16x32_bf16 v[54:57], v[152:155], v[176:179], v[54:57]
	v_mfma_f32_16x16x32_bf16 v[46:49], v[160:163], v[176:179], v[46:49]
	v_mfma_f32_16x16x32_bf16 v[38:41], v[152:155], v[184:187], v[38:41]
	v_mfma_f32_16x16x32_bf16 v[30:33], v[160:163], v[184:187], v[30:33]
	v_mfma_f32_16x16x32_bf16 v[22:25], v[152:155], v[192:195], v[22:25]
	v_mfma_f32_16x16x32_bf16 v[14:17], v[160:163], v[192:195], v[14:17]
	v_mfma_f32_16x16x32_bf16 v[62:65], v[156:159], v[172:175], v[62:65]
	v_mfma_f32_16x16x32_bf16 v[58:61], v[164:167], v[172:175], v[58:61]
	v_mfma_f32_16x16x32_bf16 v[54:57], v[156:159], v[180:183], v[54:57]
	v_mfma_f32_16x16x32_bf16 v[46:49], v[164:167], v[180:183], v[46:49]
	v_mfma_f32_16x16x32_bf16 v[38:41], v[156:159], v[188:191], v[38:41]
	v_mfma_f32_16x16x32_bf16 v[30:33], v[164:167], v[188:191], v[30:33]
	v_mfma_f32_16x16x32_bf16 v[22:25], v[156:159], v[196:199], v[22:25]
	v_mfma_f32_16x16x32_bf16 v[14:17], v[164:167], v[196:199], v[14:17]
	v_mfma_f32_16x16x32_bf16 v[50:53], v[200:203], v[168:171], v[50:53]
	v_mfma_f32_16x16x32_bf16 v[42:45], v[208:211], v[168:171], v[42:45]
	v_mfma_f32_16x16x32_bf16 v[34:37], v[200:203], v[176:179], v[34:37]
	v_mfma_f32_16x16x32_bf16 v[26:29], v[208:211], v[176:179], v[26:29]
	v_mfma_f32_16x16x32_bf16 v[18:21], v[200:203], v[184:187], v[18:21]
	v_mfma_f32_16x16x32_bf16 v[10:13], v[208:211], v[184:187], v[10:13]
	v_mfma_f32_16x16x32_bf16 v[6:9], v[200:203], v[192:195], v[6:9]
	v_mfma_f32_16x16x32_bf16 v[2:5], v[208:211], v[192:195], v[2:5]
	v_mfma_f32_16x16x32_bf16 v[50:53], v[204:207], v[172:175], v[50:53]
	v_mfma_f32_16x16x32_bf16 v[42:45], v[212:215], v[172:175], v[42:45]
	v_mfma_f32_16x16x32_bf16 v[34:37], v[204:207], v[180:183], v[34:37]
	v_mfma_f32_16x16x32_bf16 v[26:29], v[212:215], v[180:183], v[26:29]
	v_mfma_f32_16x16x32_bf16 v[18:21], v[204:207], v[188:191], v[18:21]
	v_mfma_f32_16x16x32_bf16 v[10:13], v[212:215], v[188:191], v[10:13]
	v_mfma_f32_16x16x32_bf16 v[6:9], v[204:207], v[196:199], v[6:9]
	v_mfma_f32_16x16x32_bf16 v[2:5], v[212:215], v[196:199], v[2:5]
	s_add_i32 s61, 0, 0x18000
	v_add_u32_e32 v151, s61, v146
	s_barrier
	ds_read_b128 v[152:155], v151
	ds_read_b128 v[156:159], v151 offset:1024
	ds_read_b128 v[160:163], v151 offset:2048
	ds_read_b128 v[164:167], v151 offset:3072
	ds_read_b128 v[200:203], v151 offset:16384
	ds_read_b128 v[204:207], v151 offset:17408
	ds_read_b128 v[208:211], v151 offset:18432
	ds_read_b128 v[212:215], v151 offset:19456
	s_add_u32 s28, s44, 0x100000
	s_addc_u32 s29, s45, 0
	s_mov_b32 m0, s47
	v_lshl_add_u64 v[226:227], s[28:29], 0, v[136:137]
	ds_read_b128 v[168:171], v149 offset:32768
	ds_read_b128 v[172:175], v149 offset:33792
	ds_read_b128 v[176:179], v149 offset:34816
	ds_read_b128 v[180:183], v149 offset:35840
	ds_read_b128 v[184:187], v149 offset:36864
	ds_read_b128 v[188:191], v149 offset:37888
	ds_read_b128 v[192:195], v149 offset:38912
	ds_read_b128 v[196:199], v149 offset:39936
	global_load_lds_dwordx4 v[226:227], off
	v_lshl_add_u64 v[226:227], s[28:29], 0, v[132:133]
	s_mov_b32 m0, s48
	s_nop 0
	global_load_lds_dwordx4 v[226:227], off
	s_waitcnt vmcnt(8)
	s_waitcnt lgkmcnt(0)
	s_barrier
	v_mfma_f32_16x16x32_bf16 v[126:129], v[152:155], v[168:171], v[126:129]
	v_mfma_f32_16x16x32_bf16 v[122:125], v[160:163], v[168:171], v[122:125]
	v_mfma_f32_16x16x32_bf16 v[114:117], v[152:155], v[176:179], v[114:117]
	v_mfma_f32_16x16x32_bf16 v[106:109], v[160:163], v[176:179], v[106:109]
	v_mfma_f32_16x16x32_bf16 v[98:101], v[152:155], v[184:187], v[98:101]
	v_mfma_f32_16x16x32_bf16 v[90:93], v[160:163], v[184:187], v[90:93]
	v_mfma_f32_16x16x32_bf16 v[82:85], v[152:155], v[192:195], v[82:85]
	v_mfma_f32_16x16x32_bf16 v[74:77], v[160:163], v[192:195], v[74:77]
	v_mfma_f32_16x16x32_bf16 v[126:129], v[156:159], v[172:175], v[126:129]
	v_mfma_f32_16x16x32_bf16 v[122:125], v[164:167], v[172:175], v[122:125]
	v_mfma_f32_16x16x32_bf16 v[114:117], v[156:159], v[180:183], v[114:117]
	v_mfma_f32_16x16x32_bf16 v[106:109], v[164:167], v[180:183], v[106:109]
	v_mfma_f32_16x16x32_bf16 v[98:101], v[156:159], v[188:191], v[98:101]
	v_mfma_f32_16x16x32_bf16 v[90:93], v[164:167], v[188:191], v[90:93]
	v_mfma_f32_16x16x32_bf16 v[82:85], v[156:159], v[196:199], v[82:85]
	v_mfma_f32_16x16x32_bf16 v[74:77], v[164:167], v[196:199], v[74:77]
	v_mfma_f32_16x16x32_bf16 v[118:121], v[200:203], v[168:171], v[118:121]
	v_mfma_f32_16x16x32_bf16 v[110:113], v[208:211], v[168:171], v[110:113]
	v_mfma_f32_16x16x32_bf16 v[102:105], v[200:203], v[176:179], v[102:105]
	v_mfma_f32_16x16x32_bf16 v[94:97], v[208:211], v[176:179], v[94:97]
	v_mfma_f32_16x16x32_bf16 v[86:89], v[200:203], v[184:187], v[86:89]
	v_mfma_f32_16x16x32_bf16 v[78:81], v[208:211], v[184:187], v[78:81]
	v_mfma_f32_16x16x32_bf16 v[70:73], v[200:203], v[192:195], v[70:73]
	v_mfma_f32_16x16x32_bf16 v[66:69], v[208:211], v[192:195], v[66:69]
	v_mfma_f32_16x16x32_bf16 v[118:121], v[204:207], v[172:175], v[118:121]
	v_mfma_f32_16x16x32_bf16 v[110:113], v[212:215], v[172:175], v[110:113]
	v_mfma_f32_16x16x32_bf16 v[102:105], v[204:207], v[180:183], v[102:105]
	v_mfma_f32_16x16x32_bf16 v[94:97], v[212:215], v[180:183], v[94:97]
	v_mfma_f32_16x16x32_bf16 v[86:89], v[204:207], v[188:191], v[86:89]
	v_mfma_f32_16x16x32_bf16 v[78:81], v[212:215], v[188:191], v[78:81]
	v_mfma_f32_16x16x32_bf16 v[70:73], v[204:207], v[196:199], v[70:73]
	v_mfma_f32_16x16x32_bf16 v[66:69], v[212:215], v[196:199], v[66:69]
	s_barrier
	ds_read_b128 v[168:171], v149 offset:49152
	ds_read_b128 v[172:175], v149 offset:50176
	ds_read_b128 v[176:179], v149 offset:51200
	ds_read_b128 v[180:183], v149 offset:52224
	ds_read_b128 v[184:187], v149 offset:53248
	ds_read_b128 v[188:191], v149 offset:54272
	ds_read_b128 v[192:195], v149 offset:55296
	ds_read_b128 v[196:199], v149 offset:56320
	s_add_i32 s44, 0, 0x1c000
	s_add_i32 s28, s61, s31
	v_lshl_add_u64 v[144:145], v[144:145], 0, s[12:13]
	s_mov_b32 m0, s28
	s_nop 0
	global_load_lds_dwordx4 v[144:145], off
	v_lshl_add_u64 v[144:145], v[216:217], 0, s[12:13]
	s_add_i32 m0, s28, 0x2000
	s_nop 0
	global_load_lds_dwordx4 v[144:145], off
	s_mov_b32 m0, s50
	v_lshl_add_u64 v[144:145], v[218:219], 0, s[12:13]
	global_load_lds_dwordx4 v[144:145], off
	v_lshl_add_u64 v[144:145], v[220:221], 0, s[12:13]
	s_mov_b32 m0, s51
	s_nop 0
	global_load_lds_dwordx4 v[144:145], off
	s_add_u32 s28, s40, 0x100080
	s_addc_u32 s29, s41, 0
	s_add_i32 s40, s44, s31
	v_lshl_add_u64 v[144:145], s[28:29], 0, v[134:135]
	s_mov_b32 m0, s40
	s_nop 0
	global_load_lds_dwordx4 v[144:145], off
	v_lshl_add_u64 v[144:145], s[28:29], 0, v[130:131]
	s_add_i32 m0, s40, 0x2000
	s_nop 0
	global_load_lds_dwordx4 v[144:145], off
	s_waitcnt vmcnt(8)
	s_waitcnt lgkmcnt(0)
	s_barrier
	v_mfma_f32_16x16x32_bf16 v[62:65], v[152:155], v[168:171], v[62:65]
	v_mfma_f32_16x16x32_bf16 v[58:61], v[160:163], v[168:171], v[58:61]
	v_mfma_f32_16x16x32_bf16 v[54:57], v[152:155], v[176:179], v[54:57]
	v_mfma_f32_16x16x32_bf16 v[46:49], v[160:163], v[176:179], v[46:49]
	v_mfma_f32_16x16x32_bf16 v[38:41], v[152:155], v[184:187], v[38:41]
	v_mfma_f32_16x16x32_bf16 v[30:33], v[160:163], v[184:187], v[30:33]
	v_mfma_f32_16x16x32_bf16 v[22:25], v[152:155], v[192:195], v[22:25]
	v_mfma_f32_16x16x32_bf16 v[14:17], v[160:163], v[192:195], v[14:17]
	v_mfma_f32_16x16x32_bf16 v[62:65], v[156:159], v[172:175], v[62:65]
	v_mfma_f32_16x16x32_bf16 v[58:61], v[164:167], v[172:175], v[58:61]
	v_mfma_f32_16x16x32_bf16 v[54:57], v[156:159], v[180:183], v[54:57]
	v_mfma_f32_16x16x32_bf16 v[46:49], v[164:167], v[180:183], v[46:49]
	v_mfma_f32_16x16x32_bf16 v[38:41], v[156:159], v[188:191], v[38:41]
	v_mfma_f32_16x16x32_bf16 v[30:33], v[164:167], v[188:191], v[30:33]
	v_mfma_f32_16x16x32_bf16 v[22:25], v[156:159], v[196:199], v[22:25]
	v_mfma_f32_16x16x32_bf16 v[14:17], v[164:167], v[196:199], v[14:17]
	v_mfma_f32_16x16x32_bf16 v[50:53], v[200:203], v[168:171], v[50:53]
	v_mfma_f32_16x16x32_bf16 v[42:45], v[208:211], v[168:171], v[42:45]
	v_mfma_f32_16x16x32_bf16 v[34:37], v[200:203], v[176:179], v[34:37]
	v_mfma_f32_16x16x32_bf16 v[26:29], v[208:211], v[176:179], v[26:29]
	v_mfma_f32_16x16x32_bf16 v[18:21], v[200:203], v[184:187], v[18:21]
	v_mfma_f32_16x16x32_bf16 v[10:13], v[208:211], v[184:187], v[10:13]
	v_mfma_f32_16x16x32_bf16 v[6:9], v[200:203], v[192:195], v[6:9]
	v_mfma_f32_16x16x32_bf16 v[2:5], v[208:211], v[192:195], v[2:5]
	v_mfma_f32_16x16x32_bf16 v[50:53], v[204:207], v[172:175], v[50:53]
	v_mfma_f32_16x16x32_bf16 v[42:45], v[212:215], v[172:175], v[42:45]
	v_mfma_f32_16x16x32_bf16 v[34:37], v[204:207], v[180:183], v[34:37]
	v_mfma_f32_16x16x32_bf16 v[26:29], v[212:215], v[180:183], v[26:29]
	v_mfma_f32_16x16x32_bf16 v[18:21], v[204:207], v[188:191], v[18:21]
	v_mfma_f32_16x16x32_bf16 v[10:13], v[212:215], v[188:191], v[10:13]
	v_mfma_f32_16x16x32_bf16 v[6:9], v[204:207], v[196:199], v[6:9]
	v_mfma_f32_16x16x32_bf16 v[2:5], v[212:215], v[196:199], v[2:5]
	s_add_i32 s60, s60, 2
	s_add_u32 s21, s21, 0x100
	s_addc_u32 s23, s23, 0
	s_add_u32 s38, s38, 0x100
	s_addc_u32 s39, s39, 0
	s_cmp_gt_u32 s60, 61
	s_barrier
	s_cbranch_scc0 .LBB0_4133
	s_setprio 0
	v_lshl_add_u32 v152, s36, 8, v1
	v_lshl_or_b32 v144, s59, 8, v147
	v_ashrrev_i32_e32 v153, 31, v152
	v_ashrrev_i32_e32 v145, 31, v144
	v_lshlrev_b64 v[154:155], 13, v[152:153]
	v_lshl_add_u64 v[154:155], s[8:9], 0, v[154:155]
	v_lshlrev_b64 v[156:157], 1, v[144:145]
	v_lshl_add_u64 v[144:145], v[154:155], 0, v[156:157]
	v_cvt_pk_bf16_f32 v126, v126, v127
	v_cvt_pk_bf16_f32 v127, v128, v129
	v_cvt_pk_bf16_f32 v128, v122, v123
	v_cvt_pk_bf16_f32 v129, v124, v125
	global_store_dwordx4 v[144:145], v[126:129], off
	v_cvt_pk_bf16_f32 v118, v118, v119
	v_cvt_pk_bf16_f32 v119, v120, v121
	v_cvt_pk_bf16_f32 v120, v110, v111
	v_or_b32_e32 v110, 16, v152
	v_ashrrev_i32_e32 v111, 31, v110
	v_lshlrev_b64 v[110:111], 13, v[110:111]
	v_lshl_add_u64 v[110:111], s[8:9], 0, v[110:111]
	v_cvt_pk_bf16_f32 v121, v112, v113
	global_store_dwordx4 v[144:145], v[118:121], off offset:256
	s_mov_b32 s36, s22
	s_mov_b32 s59, s20
	v_lshl_add_u64 v[118:119], v[110:111], 0, v[156:157]
	v_cvt_pk_bf16_f32 v110, v114, v115
	v_cvt_pk_bf16_f32 v111, v116, v117
	v_cvt_pk_bf16_f32 v112, v106, v107
	v_cvt_pk_bf16_f32 v113, v108, v109
	global_store_dwordx4 v[118:119], v[110:113], off
	v_cvt_pk_bf16_f32 v102, v102, v103
	v_cvt_pk_bf16_f32 v103, v104, v105
	v_cvt_pk_bf16_f32 v104, v94, v95
	v_or_b32_e32 v94, 32, v152
	v_ashrrev_i32_e32 v95, 31, v94
	v_lshlrev_b64 v[94:95], 13, v[94:95]
	v_lshl_add_u64 v[94:95], s[8:9], 0, v[94:95]
	v_cvt_pk_bf16_f32 v105, v96, v97
	global_store_dwordx4 v[118:119], v[102:105], off offset:256
	s_mov_b64 s[40:41], s[34:35]
	s_mov_b64 s[38:39], s[26:27]
	v_lshl_add_u64 v[102:103], v[94:95], 0, v[156:157]
	v_cvt_pk_bf16_f32 v94, v98, v99
	v_cvt_pk_bf16_f32 v95, v100, v101
	v_cvt_pk_bf16_f32 v96, v90, v91
	v_cvt_pk_bf16_f32 v97, v92, v93
	global_store_dwordx4 v[102:103], v[94:97], off
	v_cvt_pk_bf16_f32 v86, v86, v87
	v_cvt_pk_bf16_f32 v87, v88, v89
	v_cvt_pk_bf16_f32 v88, v78, v79
	v_or_b32_e32 v78, 48, v152
	v_ashrrev_i32_e32 v79, 31, v78
	v_lshlrev_b64 v[78:79], 13, v[78:79]
	v_lshl_add_u64 v[78:79], s[8:9], 0, v[78:79]
	v_cvt_pk_bf16_f32 v89, v80, v81
	global_store_dwordx4 v[102:103], v[86:89], off offset:256
	s_nop 1
	v_lshl_add_u64 v[86:87], v[78:79], 0, v[156:157]
	v_cvt_pk_bf16_f32 v78, v82, v83
	v_cvt_pk_bf16_f32 v79, v84, v85
	v_cvt_pk_bf16_f32 v80, v74, v75
	v_cvt_pk_bf16_f32 v81, v76, v77
	global_store_dwordx4 v[86:87], v[78:81], off
	v_cvt_pk_bf16_f32 v70, v70, v71
	v_cvt_pk_bf16_f32 v71, v72, v73
	v_cvt_pk_bf16_f32 v72, v66, v67
	v_cvt_pk_bf16_f32 v73, v68, v69
	global_store_dwordx4 v[86:87], v[70:73], off offset:256
	v_cvt_pk_bf16_f32 v62, v62, v63
	v_cvt_pk_bf16_f32 v63, v64, v65
	v_cvt_pk_bf16_f32 v64, v58, v59
	v_add_co_u32_e32 v58, vcc, s55, v144
	v_lshl_add_u64 v[66:67], v[144:145], 0, s[6:7]
	s_nop 0
	v_addc_co_u32_e32 v59, vcc, 0, v145, vcc
	v_cvt_pk_bf16_f32 v65, v60, v61
	global_store_dwordx4 v[58:59], v[62:65], off
	v_cvt_pk_bf16_f32 v50, v50, v51
	v_cvt_pk_bf16_f32 v51, v52, v53
	v_cvt_pk_bf16_f32 v52, v42, v43
	v_cvt_pk_bf16_f32 v53, v44, v45
	global_store_dwordx4 v[66:67], v[50:53], off offset:256
	v_cvt_pk_bf16_f32 v42, v54, v55
	v_cvt_pk_bf16_f32 v43, v56, v57
	v_cvt_pk_bf16_f32 v44, v46, v47
	v_add_co_u32_e32 v46, vcc, s56, v144
	s_nop 0
	v_lshl_add_u64 v[50:51], v[144:145], 0, s[14:15]
	v_addc_co_u32_e32 v47, vcc, 0, v145, vcc
	v_cvt_pk_bf16_f32 v45, v48, v49
	global_store_dwordx4 v[46:47], v[42:45], off
	v_cvt_pk_bf16_f32 v34, v34, v35
	v_cvt_pk_bf16_f32 v35, v36, v37
	v_cvt_pk_bf16_f32 v36, v26, v27
	v_cvt_pk_bf16_f32 v37, v28, v29
	global_store_dwordx4 v[50:51], v[34:37], off offset:256
	v_cvt_pk_bf16_f32 v26, v38, v39
	v_cvt_pk_bf16_f32 v27, v40, v41
	v_cvt_pk_bf16_f32 v28, v30, v31
	v_add_co_u32_e32 v30, vcc, s57, v144
	s_nop 0
	v_lshl_add_u64 v[34:35], v[144:145], 0, s[16:17]
	v_addc_co_u32_e32 v31, vcc, 0, v145, vcc
	v_cvt_pk_bf16_f32 v29, v32, v33
	global_store_dwordx4 v[30:31], v[26:29], off
	v_cvt_pk_bf16_f32 v18, v18, v19
	v_cvt_pk_bf16_f32 v19, v20, v21
	v_cvt_pk_bf16_f32 v20, v10, v11
	v_cvt_pk_bf16_f32 v21, v12, v13
	global_store_dwordx4 v[34:35], v[18:21], off offset:256
	v_cvt_pk_bf16_f32 v10, v22, v23
	v_cvt_pk_bf16_f32 v11, v24, v25
	v_cvt_pk_bf16_f32 v12, v14, v15
	v_add_co_u32_e32 v14, vcc, s58, v144
	s_nop 0
	v_lshl_add_u64 v[18:19], v[144:145], 0, s[18:19]
	v_addc_co_u32_e32 v15, vcc, 0, v145, vcc
	s_and_b64 vcc, exec, s[4:5]
	v_cvt_pk_bf16_f32 v13, v16, v17
	global_store_dwordx4 v[14:15], v[10:13], off
	v_cvt_pk_bf16_f32 v6, v6, v7
	v_cvt_pk_bf16_f32 v7, v8, v9
	v_cvt_pk_bf16_f32 v8, v2, v3
	v_cvt_pk_bf16_f32 v9, v4, v5
	global_store_dwordx4 v[18:19], v[6:9], off offset:256
	s_cbranch_vccz .LBB0_4126
	s_waitcnt vmcnt(0)
	s_cmpk_gt_u32 s11, 0xff
	s_cbranch_scc1 .LBB0_4137
	s_barrier
